# SWIGLU/MIX/VT epilogue stores as global_store instead of flat_store
# baseline (speedup 1.0000x reference)
; __device__ __forceinline__ unsigned cvtpk(float lo, float hi) { f32x2_t v = {lo, hi}; bf16x2_t b = __builtin_convertvector(v, bf16x2_t); return __builtin_bit_cast(unsigned, b); }
;     __device__ __forceinline__ void operator()(const f32x4 (&acc)[2][2][4][2], const Unit& u, int wr, int wc, int fr, int fq) const {
;     ...
;         } else if (mode == M_VT) {
;             f32x4 cv[2][2];
; #pragma unroll
;             for (int bj = 0; bj < 2; ++bj)
; #pragma unroll
;                 for (int n = 0; n < 2; ++n) { const f32x4 sv = *(const f32x4*)(rs + u.pn * BM + bj * HALF + cw + 4 * n);
; #pragma unroll
;                     for (int e = 0; e < 4; ++e) cv[bj][n][e] = __builtin_amdgcn_rsqf(sv[e] * (1.0f / 1024.0f) + 1e-6f); }
; #pragma unroll
;             for (int ai = 0; ai < 2; ++ai)
; #pragma unroll
;                 for (int m = 0; m < 4; ++m) { bf16_t* rowp = O + (size_t)(row0 + ai * HALF + m * 16) * ldc + u.pn * BM + cw;
; #pragma unroll
;                     for (int bj = 0; bj < 2; ++bj) {
;                         if (u.pm < 4) {
;                             const f32x4 v0 = acc[ai][bj][m][0] * cv[bj][0], v1 = acc[ai][bj][m][1] * cv[bj][1];
;                             bf16_t* gb = rowp + bj * HALF - 8 * (fq & 1) + 4 * (fq & 1);
;                             u32x2 w0, w1; w0.x = cvtpk(v0[0], v0[1]); w0.y = cvtpk(v0[2], v0[3]); w1.x = cvtpk(v1[0], v1[1]); w1.y = cvtpk(v1[2], v1[3]);
;                             *(u32x2*)gb = w0; *(u32x2*)(gb + 8) = w1;
;                         } else store8(rowp + bj * HALF, acc[ai][bj][m][0] * cv[bj][0], acc[ai][bj][m][1] * cv[bj][1]); } }
.LBB0_420:
	s_and_b64 vcc, exec, s[6:7]
	s_cbranch_vccz .LBB0_485
	s_lshl_b32 s38, s40, 8
	s_ashr_i32 s39, s38, 31
	v_lshl_add_u64 v[128:129], s[38:39], 2, v[154:155]
	flat_load_dwordx4 v[136:139], v[128:129]
	flat_load_dwordx4 v[166:169], v[128:129] offset:16
	flat_load_dwordx4 v[132:135], v[128:129] offset:512
	s_nop 0
	flat_load_dwordx4 v[128:131], v[128:129] offset:528
	v_mad_i64_i32 v[170:171], s[6:7], s82, v164, 0
	v_lshl_add_u64 v[170:171], v[170:171], 1, s[84:85]
	v_lshl_add_u64 v[170:171], s[38:39], 1, v[170:171]
	v_lshl_add_u64 v[174:175], v[148:149], 1, v[170:171]
	s_cmp_gt_i32 s48, 3
	s_cselect_b64 s[98:99], -1, 0
	s_mov_b64 s[6:7], -1
	s_and_b64 vcc, exec, s[98:99]
	s_waitcnt vmcnt(0) lgkmcnt(0)
	v_fmamk_f32 v136, v136, 0x3a800000, v237
	v_fmamk_f32 v137, v137, 0x3a800000, v237
	v_fmamk_f32 v138, v138, 0x3a800000, v237
	v_fmamk_f32 v139, v139, 0x3a800000, v237
	v_fmamk_f32 v165, v166, 0x3a800000, v237
	v_fmamk_f32 v167, v167, 0x3a800000, v237
	v_fmamk_f32 v168, v168, 0x3a800000, v237
	v_fmamk_f32 v169, v169, 0x3a800000, v237
	v_rsq_f32_e32 v170, v136
	v_rsq_f32_e32 v171, v137
	v_rsq_f32_e32 v172, v138
	v_rsq_f32_e32 v173, v139
	v_rsq_f32_e32 v166, v165
	v_rsq_f32_e32 v168, v168
	v_rsq_f32_e32 v169, v169
	v_rsq_f32_e32 v167, v167
	v_pk_mul_f32 v[138:139], v[126:127], v[172:173]
	v_pk_mul_f32 v[136:137], v[124:125], v[170:171]
	v_pk_mul_f32 v[178:179], v[122:123], v[168:169]
	v_pk_mul_f32 v[182:183], v[120:121], v[166:167]
	v_cvt_pk_bf16_f32 v136, v136, v137
	v_cvt_pk_bf16_f32 v137, v138, v139
	v_cvt_pk_bf16_f32 v138, v182, v183
	v_cvt_pk_bf16_f32 v139, v178, v179
	s_cbranch_vccz .LBB0_423
	global_store_dwordx4 v[174:175], v[136:139], off
	s_mov_b64 s[6:7], 0
.LBB0_423:
	v_lshl_add_u64 v[178:179], v[150:151], 1, v[174:175]
	v_lshlrev_b32_e32 v176, 1, v152
	s_andn2_b64 vcc, exec, s[6:7]
	v_lshl_add_u64 v[178:179], v[178:179], 0, v[176:177]
	s_cbranch_vccnz .LBB0_425
	global_store_dwordx2 v[178:179], v[136:137], off
	global_store_dwordx2 v[178:179], v[138:139], off offset:16
.LBB0_425:
	v_fmamk_f32 v128, v128, 0x3a800000, v237
	v_fmamk_f32 v132, v132, 0x3a800000, v237
	v_rsq_f32_e32 v138, v128
	v_fmamk_f32 v128, v129, 0x3a800000, v237
	v_rsq_f32_e32 v136, v132
	v_fmamk_f32 v132, v133, 0x3a800000, v237
	v_rsq_f32_e32 v139, v128
	v_fmamk_f32 v128, v130, 0x3a800000, v237
	v_rsq_f32_e32 v137, v132
	v_fmamk_f32 v132, v134, 0x3a800000, v237
	v_fmamk_f32 v133, v135, 0x3a800000, v237
	v_rsq_f32_e32 v134, v128
	v_fmamk_f32 v128, v131, 0x3a800000, v237
	v_rsq_f32_e32 v132, v132
	v_rsq_f32_e32 v133, v133
	v_rsq_f32_e32 v135, v128
	v_cndmask_b32_e64 v128, 0, 1, s[98:99]
	s_mov_b64 s[48:49], -1
	v_cmp_ne_u32_e64 s[6:7], 1, v128
	s_andn2_b64 vcc, exec, s[98:99]
	v_pk_mul_f32 v[130:131], v[108:109], v[136:137]
	v_pk_mul_f32 v[128:129], v[104:105], v[138:139]
	s_cbranch_vccnz .LBB0_427
	v_pk_mul_f32 v[184:185], v[110:111], v[132:133]
	v_pk_mul_f32 v[186:187], v[106:107], v[134:135]
	v_cvt_pk_bf16_f32 v182, v130, v131
	v_cvt_pk_bf16_f32 v183, v184, v185
	v_cvt_pk_bf16_f32 v184, v128, v129
	v_cvt_pk_bf16_f32 v185, v186, v187
	s_mov_b64 s[48:49], 0
	global_store_dwordx4 v[174:175], v[182:185], off offset:256
.LBB0_427:
	s_andn2_b64 vcc, exec, s[48:49]
	s_cbranch_vccnz .LBB0_429
	v_pk_mul_f32 v[174:175], v[110:111], v[132:133]
	v_pk_mul_f32 v[182:183], v[106:107], v[134:135]
	v_cvt_pk_bf16_f32 v130, v130, v131
	v_cvt_pk_bf16_f32 v131, v174, v175
	v_cvt_pk_bf16_f32 v128, v128, v129
	v_cvt_pk_bf16_f32 v129, v182, v183
	global_store_dwordx2 v[178:179], v[130:131], off offset:256
	global_store_dwordx2 v[178:179], v[128:129], off offset:272
.LBB0_429:
	v_or_b32_e32 v128, 16, v164
	v_mad_i64_i32 v[128:129], s[48:49], s82, v128, 0
	v_lshl_add_u64 v[128:129], v[128:129], 1, s[84:85]
	v_lshl_add_u64 v[128:129], s[38:39], 1, v[128:129]
	v_lshl_add_u64 v[174:175], v[148:149], 1, v[128:129]
	v_pk_mul_f32 v[130:131], v[118:119], v[172:173]
	v_pk_mul_f32 v[128:129], v[116:117], v[170:171]
	v_pk_mul_f32 v[178:179], v[114:115], v[168:169]
	v_pk_mul_f32 v[182:183], v[112:113], v[166:167]
	v_cvt_pk_bf16_f32 v128, v128, v129
	v_cvt_pk_bf16_f32 v129, v130, v131
	v_cvt_pk_bf16_f32 v130, v182, v183
	v_cvt_pk_bf16_f32 v131, v178, v179
	s_and_b64 vcc, exec, s[6:7]
	s_mov_b64 s[48:49], -1
	s_cbranch_vccnz .LBB0_431
	s_mov_b64 s[48:49], 0
	global_store_dwordx4 v[174:175], v[128:131], off
.LBB0_431:
	v_lshl_add_u64 v[178:179], v[150:151], 1, v[174:175]
	s_andn2_b64 vcc, exec, s[48:49]
	v_lshl_add_u64 v[178:179], v[178:179], 0, v[176:177]
	s_cbranch_vccnz .LBB0_433
	global_store_dwordx2 v[178:179], v[128:129], off
	global_store_dwordx2 v[178:179], v[130:131], off offset:16
.LBB0_433:
	s_mov_b64 s[48:49], -1
	s_and_b64 vcc, exec, s[6:7]
	v_pk_mul_f32 v[130:131], v[92:93], v[136:137]
	v_pk_mul_f32 v[128:129], v[88:89], v[138:139]
	s_cbranch_vccnz .LBB0_435
	v_pk_mul_f32 v[184:185], v[94:95], v[132:133]
	v_pk_mul_f32 v[186:187], v[90:91], v[134:135]
	v_cvt_pk_bf16_f32 v182, v130, v131
	v_cvt_pk_bf16_f32 v183, v184, v185
	v_cvt_pk_bf16_f32 v184, v128, v129
	v_cvt_pk_bf16_f32 v185, v186, v187
	s_mov_b64 s[48:49], 0
	global_store_dwordx4 v[174:175], v[182:185], off offset:256
.LBB0_435:
	s_andn2_b64 vcc, exec, s[48:49]
	s_cbranch_vccnz .LBB0_437
	v_pk_mul_f32 v[174:175], v[94:95], v[132:133]
	v_pk_mul_f32 v[182:183], v[90:91], v[134:135]
	v_cvt_pk_bf16_f32 v130, v130, v131
	v_cvt_pk_bf16_f32 v131, v174, v175
	v_cvt_pk_bf16_f32 v128, v128, v129
	v_cvt_pk_bf16_f32 v129, v182, v183
	global_store_dwordx2 v[178:179], v[130:131], off offset:256
	global_store_dwordx2 v[178:179], v[128:129], off offset:272
.LBB0_437:
	v_or_b32_e32 v128, 32, v164
	v_mad_i64_i32 v[128:129], s[48:49], s82, v128, 0
	v_lshl_add_u64 v[128:129], v[128:129], 1, s[84:85]
	v_lshl_add_u64 v[128:129], s[38:39], 1, v[128:129]
	v_lshl_add_u64 v[174:175], v[148:149], 1, v[128:129]
	v_pk_mul_f32 v[130:131], v[102:103], v[172:173]
	v_pk_mul_f32 v[128:129], v[100:101], v[170:171]
	v_pk_mul_f32 v[178:179], v[98:99], v[168:169]
	v_pk_mul_f32 v[182:183], v[96:97], v[166:167]
	v_cvt_pk_bf16_f32 v128, v128, v129
	v_cvt_pk_bf16_f32 v129, v130, v131
	v_cvt_pk_bf16_f32 v130, v182, v183
	v_cvt_pk_bf16_f32 v131, v178, v179
	s_and_b64 vcc, exec, s[6:7]
	s_mov_b64 s[48:49], -1
	s_cbranch_vccnz .LBB0_439
	s_mov_b64 s[48:49], 0
	global_store_dwordx4 v[174:175], v[128:131], off

; __device__ __forceinline__ unsigned cvtpk(float lo, float hi) { f32x2_t v = {lo, hi}; bf16x2_t b = __builtin_convertvector(v, bf16x2_t); return __builtin_bit_cast(unsigned, b); }
;     __device__ __forceinline__ void operator()(const f32x4 (&acc)[2][2][4][2], const Unit& u, int wr, int wc, int fr, int fq) const {
;     ...
;             for (int ai = 0; ai < 2; ++ai)
; #pragma unroll
;                 for (int m = 0; m < 4; ++m) { bf16_t* rowp = O + (size_t)(row0 + ai * HALF + m * 16) * ldc + u.pn * BM + cw;
; #pragma unroll
;                     for (int bj = 0; bj < 2; ++bj) {
;                         if (u.pm < 4) {
;                             const f32x4 v0 = acc[ai][bj][m][0] * cv[bj][0], v1 = acc[ai][bj][m][1] * cv[bj][1];
;                             bf16_t* gb = rowp + bj * HALF - 8 * (fq & 1) + 4 * (fq & 1);
;                             u32x2 w0, w1; w0.x = cvtpk(v0[0], v0[1]); w0.y = cvtpk(v0[2], v0[3]); w1.x = cvtpk(v1[0], v1[1]); w1.y = cvtpk(v1[2], v1[3]);
;                             *(u32x2*)gb = w0; *(u32x2*)(gb + 8) = w1;
;                         } else store8(rowp + bj * HALF, acc[ai][bj][m][0] * cv[bj][0], acc[ai][bj][m][1] * cv[bj][1]); } }
.LBB0_441:
	s_mov_b64 s[48:49], -1
	s_and_b64 vcc, exec, s[6:7]
	v_pk_mul_f32 v[130:131], v[76:77], v[136:137]
	v_pk_mul_f32 v[128:129], v[72:73], v[138:139]
	s_cbranch_vccnz .LBB0_443
	v_pk_mul_f32 v[184:185], v[78:79], v[132:133]
	v_pk_mul_f32 v[186:187], v[74:75], v[134:135]
	v_cvt_pk_bf16_f32 v182, v130, v131
	v_cvt_pk_bf16_f32 v183, v184, v185
	v_cvt_pk_bf16_f32 v184, v128, v129
	v_cvt_pk_bf16_f32 v185, v186, v187
	s_mov_b64 s[48:49], 0
	global_store_dwordx4 v[174:175], v[182:185], off offset:256
.LBB0_443:
	s_andn2_b64 vcc, exec, s[48:49]
	s_cbranch_vccnz .LBB0_445
	v_pk_mul_f32 v[174:175], v[78:79], v[132:133]
	v_pk_mul_f32 v[182:183], v[74:75], v[134:135]
	v_cvt_pk_bf16_f32 v130, v130, v131
	v_cvt_pk_bf16_f32 v131, v174, v175
	v_cvt_pk_bf16_f32 v128, v128, v129
	v_cvt_pk_bf16_f32 v129, v182, v183
	global_store_dwordx2 v[178:179], v[130:131], off offset:256
	global_store_dwordx2 v[178:179], v[128:129], off offset:272
.LBB0_445:
	v_or_b32_e32 v128, 48, v164
	v_mad_i64_i32 v[128:129], s[48:49], s82, v128, 0
	v_lshl_add_u64 v[128:129], v[128:129], 1, s[84:85]
	v_lshl_add_u64 v[128:129], s[38:39], 1, v[128:129]
	v_lshl_add_u64 v[174:175], v[148:149], 1, v[128:129]
	v_pk_mul_f32 v[130:131], v[86:87], v[172:173]
	v_pk_mul_f32 v[128:129], v[84:85], v[170:171]
	v_pk_mul_f32 v[178:179], v[82:83], v[168:169]
	v_pk_mul_f32 v[182:183], v[80:81], v[166:167]
	v_cvt_pk_bf16_f32 v128, v128, v129
	v_cvt_pk_bf16_f32 v129, v130, v131
	v_cvt_pk_bf16_f32 v130, v182, v183
	v_cvt_pk_bf16_f32 v131, v178, v179
	s_and_b64 vcc, exec, s[6:7]
	s_mov_b64 s[48:49], -1
	s_cbranch_vccnz .LBB0_447
	s_mov_b64 s[48:49], 0
	global_store_dwordx4 v[174:175], v[128:131], off

; __device__ __forceinline__ unsigned cvtpk(float lo, float hi) { f32x2_t v = {lo, hi}; bf16x2_t b = __builtin_convertvector(v, bf16x2_t); return __builtin_bit_cast(unsigned, b); }
;     __device__ __forceinline__ void operator()(const f32x4 (&acc)[2][2][4][2], const Unit& u, int wr, int wc, int fr, int fq) const {
;     ...
;             for (int ai = 0; ai < 2; ++ai)
; #pragma unroll
;                 for (int m = 0; m < 4; ++m) { bf16_t* rowp = O + (size_t)(row0 + ai * HALF + m * 16) * ldc + u.pn * BM + cw;
; #pragma unroll
;                     for (int bj = 0; bj < 2; ++bj) {
;                         if (u.pm < 4) {
;                             const f32x4 v0 = acc[ai][bj][m][0] * cv[bj][0], v1 = acc[ai][bj][m][1] * cv[bj][1];
;                             bf16_t* gb = rowp + bj * HALF - 8 * (fq & 1) + 4 * (fq & 1);
;                             u32x2 w0, w1; w0.x = cvtpk(v0[0], v0[1]); w0.y = cvtpk(v0[2], v0[3]); w1.x = cvtpk(v1[0], v1[1]); w1.y = cvtpk(v1[2], v1[3]);
;                             *(u32x2*)gb = w0; *(u32x2*)(gb + 8) = w1;
;                         } else store8(rowp + bj * HALF, acc[ai][bj][m][0] * cv[bj][0], acc[ai][bj][m][1] * cv[bj][1]); } }
.LBB0_449:
	s_mov_b64 s[48:49], -1
	s_and_b64 vcc, exec, s[6:7]
	v_pk_mul_f32 v[130:131], v[68:69], v[136:137]
	v_pk_mul_f32 v[128:129], v[64:65], v[138:139]
	s_cbranch_vccnz .LBB0_451
	v_pk_mul_f32 v[184:185], v[70:71], v[132:133]
	v_pk_mul_f32 v[186:187], v[66:67], v[134:135]
	v_cvt_pk_bf16_f32 v182, v130, v131
	v_cvt_pk_bf16_f32 v183, v184, v185
	v_cvt_pk_bf16_f32 v184, v128, v129
	v_cvt_pk_bf16_f32 v185, v186, v187
	s_mov_b64 s[48:49], 0
	global_store_dwordx4 v[174:175], v[182:185], off offset:256
.LBB0_451:
	s_andn2_b64 vcc, exec, s[48:49]
	s_cbranch_vccnz .LBB0_453
	v_pk_mul_f32 v[174:175], v[70:71], v[132:133]
	v_pk_mul_f32 v[182:183], v[66:67], v[134:135]
	v_cvt_pk_bf16_f32 v130, v130, v131
	v_cvt_pk_bf16_f32 v131, v174, v175
	v_cvt_pk_bf16_f32 v128, v128, v129
	v_cvt_pk_bf16_f32 v129, v182, v183
	global_store_dwordx2 v[178:179], v[130:131], off offset:256
	global_store_dwordx2 v[178:179], v[128:129], off offset:272
.LBB0_453:
	v_add_u32_e32 v128, 0x80, v164
	v_mad_i64_i32 v[128:129], s[48:49], s82, v128, 0
	v_lshl_add_u64 v[128:129], v[128:129], 1, s[84:85]
	v_lshl_add_u64 v[128:129], s[38:39], 1, v[128:129]
	v_lshl_add_u64 v[174:175], v[148:149], 1, v[128:129]
	v_pk_mul_f32 v[130:131], v[62:63], v[172:173]
	v_pk_mul_f32 v[128:129], v[60:61], v[170:171]
	v_pk_mul_f32 v[178:179], v[58:59], v[168:169]
	v_pk_mul_f32 v[182:183], v[56:57], v[166:167]
	v_cvt_pk_bf16_f32 v128, v128, v129
	v_cvt_pk_bf16_f32 v129, v130, v131
	v_cvt_pk_bf16_f32 v130, v182, v183
	v_cvt_pk_bf16_f32 v131, v178, v179
	s_and_b64 vcc, exec, s[6:7]
	s_mov_b64 s[48:49], -1
	s_cbranch_vccnz .LBB0_455
	s_mov_b64 s[48:49], 0
	global_store_dwordx4 v[174:175], v[128:131], off

; __device__ __forceinline__ unsigned cvtpk(float lo, float hi) { f32x2_t v = {lo, hi}; bf16x2_t b = __builtin_convertvector(v, bf16x2_t); return __builtin_bit_cast(unsigned, b); }
;     __device__ __forceinline__ void operator()(const f32x4 (&acc)[2][2][4][2], const Unit& u, int wr, int wc, int fr, int fq) const {
;     ...
;             for (int ai = 0; ai < 2; ++ai)
; #pragma unroll
;                 for (int m = 0; m < 4; ++m) { bf16_t* rowp = O + (size_t)(row0 + ai * HALF + m * 16) * ldc + u.pn * BM + cw;
; #pragma unroll
;                     for (int bj = 0; bj < 2; ++bj) {
;                         if (u.pm < 4) {
;                             const f32x4 v0 = acc[ai][bj][m][0] * cv[bj][0], v1 = acc[ai][bj][m][1] * cv[bj][1];
;                             bf16_t* gb = rowp + bj * HALF - 8 * (fq & 1) + 4 * (fq & 1);
;                             u32x2 w0, w1; w0.x = cvtpk(v0[0], v0[1]); w0.y = cvtpk(v0[2], v0[3]); w1.x = cvtpk(v1[0], v1[1]); w1.y = cvtpk(v1[2], v1[3]);
;                             *(u32x2*)gb = w0; *(u32x2*)(gb + 8) = w1;
;                         } else store8(rowp + bj * HALF, acc[ai][bj][m][0] * cv[bj][0], acc[ai][bj][m][1] * cv[bj][1]); } }
.LBB0_457:
	s_mov_b64 s[48:49], -1
	s_and_b64 vcc, exec, s[6:7]
	v_pk_mul_f32 v[130:131], v[44:45], v[136:137]
	v_pk_mul_f32 v[128:129], v[40:41], v[138:139]
	s_cbranch_vccnz .LBB0_459
	v_pk_mul_f32 v[184:185], v[46:47], v[132:133]
	v_pk_mul_f32 v[186:187], v[42:43], v[134:135]
	v_cvt_pk_bf16_f32 v182, v130, v131
	v_cvt_pk_bf16_f32 v183, v184, v185
	v_cvt_pk_bf16_f32 v184, v128, v129
	v_cvt_pk_bf16_f32 v185, v186, v187
	s_mov_b64 s[48:49], 0
	global_store_dwordx4 v[174:175], v[182:185], off offset:256
.LBB0_459:
	s_andn2_b64 vcc, exec, s[48:49]
	s_cbranch_vccnz .LBB0_461
	v_pk_mul_f32 v[174:175], v[46:47], v[132:133]
	v_pk_mul_f32 v[182:183], v[42:43], v[134:135]
	v_cvt_pk_bf16_f32 v130, v130, v131
	v_cvt_pk_bf16_f32 v131, v174, v175
	v_cvt_pk_bf16_f32 v128, v128, v129
	v_cvt_pk_bf16_f32 v129, v182, v183
	global_store_dwordx2 v[178:179], v[130:131], off offset:256
	global_store_dwordx2 v[178:179], v[128:129], off offset:272
.LBB0_461:
	v_add_u32_e32 v128, 0x90, v164
	v_mad_i64_i32 v[128:129], s[48:49], s82, v128, 0
	v_lshl_add_u64 v[128:129], v[128:129], 1, s[84:85]
	v_lshl_add_u64 v[128:129], s[38:39], 1, v[128:129]
	v_lshl_add_u64 v[174:175], v[148:149], 1, v[128:129]
	v_pk_mul_f32 v[130:131], v[54:55], v[172:173]
	v_pk_mul_f32 v[128:129], v[52:53], v[170:171]
	v_pk_mul_f32 v[178:179], v[50:51], v[168:169]
	v_pk_mul_f32 v[182:183], v[48:49], v[166:167]
	v_cvt_pk_bf16_f32 v128, v128, v129
	v_cvt_pk_bf16_f32 v129, v130, v131
	v_cvt_pk_bf16_f32 v130, v182, v183
	v_cvt_pk_bf16_f32 v131, v178, v179
	s_and_b64 vcc, exec, s[6:7]
	s_mov_b64 s[48:49], -1
	s_cbranch_vccnz .LBB0_463
	s_mov_b64 s[48:49], 0
	global_store_dwordx4 v[174:175], v[128:131], off

; __device__ __forceinline__ unsigned cvtpk(float lo, float hi) { f32x2_t v = {lo, hi}; bf16x2_t b = __builtin_convertvector(v, bf16x2_t); return __builtin_bit_cast(unsigned, b); }
;     __device__ __forceinline__ void operator()(const f32x4 (&acc)[2][2][4][2], const Unit& u, int wr, int wc, int fr, int fq) const {
;     ...
;             for (int ai = 0; ai < 2; ++ai)
; #pragma unroll
;                 for (int m = 0; m < 4; ++m) { bf16_t* rowp = O + (size_t)(row0 + ai * HALF + m * 16) * ldc + u.pn * BM + cw;
; #pragma unroll
;                     for (int bj = 0; bj < 2; ++bj) {
;                         if (u.pm < 4) {
;                             const f32x4 v0 = acc[ai][bj][m][0] * cv[bj][0], v1 = acc[ai][bj][m][1] * cv[bj][1];
;                             bf16_t* gb = rowp + bj * HALF - 8 * (fq & 1) + 4 * (fq & 1);
;                             u32x2 w0, w1; w0.x = cvtpk(v0[0], v0[1]); w0.y = cvtpk(v0[2], v0[3]); w1.x = cvtpk(v1[0], v1[1]); w1.y = cvtpk(v1[2], v1[3]);
;                             *(u32x2*)gb = w0; *(u32x2*)(gb + 8) = w1;
;                         } else store8(rowp + bj * HALF, acc[ai][bj][m][0] * cv[bj][0], acc[ai][bj][m][1] * cv[bj][1]); } }
.LBB0_465:
	s_mov_b64 s[48:49], -1
	s_and_b64 vcc, exec, s[6:7]
	v_pk_mul_f32 v[130:131], v[28:29], v[136:137]
	v_pk_mul_f32 v[128:129], v[24:25], v[138:139]
	s_cbranch_vccnz .LBB0_467
	v_pk_mul_f32 v[184:185], v[30:31], v[132:133]
	v_pk_mul_f32 v[186:187], v[26:27], v[134:135]
	v_cvt_pk_bf16_f32 v182, v130, v131
	v_cvt_pk_bf16_f32 v183, v184, v185
	v_cvt_pk_bf16_f32 v184, v128, v129
	v_cvt_pk_bf16_f32 v185, v186, v187
	s_mov_b64 s[48:49], 0
	global_store_dwordx4 v[174:175], v[182:185], off offset:256
.LBB0_467:
	s_andn2_b64 vcc, exec, s[48:49]
	s_cbranch_vccnz .LBB0_469
	v_pk_mul_f32 v[174:175], v[30:31], v[132:133]
	v_pk_mul_f32 v[182:183], v[26:27], v[134:135]
	v_cvt_pk_bf16_f32 v130, v130, v131
	v_cvt_pk_bf16_f32 v131, v174, v175
	v_cvt_pk_bf16_f32 v128, v128, v129
	v_cvt_pk_bf16_f32 v129, v182, v183
	global_store_dwordx2 v[178:179], v[130:131], off offset:256
	global_store_dwordx2 v[178:179], v[128:129], off offset:272
.LBB0_469:
	v_add_u32_e32 v128, 0xa0, v164
	v_mad_i64_i32 v[128:129], s[48:49], s82, v128, 0
	v_lshl_add_u64 v[128:129], v[128:129], 1, s[84:85]
	v_lshl_add_u64 v[128:129], s[38:39], 1, v[128:129]
	v_lshl_add_u64 v[174:175], v[148:149], 1, v[128:129]
	v_pk_mul_f32 v[130:131], v[38:39], v[172:173]
	v_pk_mul_f32 v[128:129], v[36:37], v[170:171]
	v_pk_mul_f32 v[178:179], v[34:35], v[168:169]
	v_pk_mul_f32 v[182:183], v[32:33], v[166:167]
	v_cvt_pk_bf16_f32 v128, v128, v129
	v_cvt_pk_bf16_f32 v129, v130, v131
	v_cvt_pk_bf16_f32 v130, v182, v183
	v_cvt_pk_bf16_f32 v131, v178, v179
	s_and_b64 vcc, exec, s[6:7]
	s_mov_b64 s[48:49], -1
	s_cbranch_vccnz .LBB0_471
	s_mov_b64 s[48:49], 0
	global_store_dwordx4 v[174:175], v[128:131], off

; __device__ __forceinline__ unsigned cvtpk(float lo, float hi) { f32x2_t v = {lo, hi}; bf16x2_t b = __builtin_convertvector(v, bf16x2_t); return __builtin_bit_cast(unsigned, b); }
;     __device__ __forceinline__ void operator()(const f32x4 (&acc)[2][2][4][2], const Unit& u, int wr, int wc, int fr, int fq) const {
;     ...
;             for (int ai = 0; ai < 2; ++ai)
; #pragma unroll
;                 for (int m = 0; m < 4; ++m) { bf16_t* rowp = O + (size_t)(row0 + ai * HALF + m * 16) * ldc + u.pn * BM + cw;
; #pragma unroll
;                     for (int bj = 0; bj < 2; ++bj) {
;                         if (u.pm < 4) {
;                             const f32x4 v0 = acc[ai][bj][m][0] * cv[bj][0], v1 = acc[ai][bj][m][1] * cv[bj][1];
;                             bf16_t* gb = rowp + bj * HALF - 8 * (fq & 1) + 4 * (fq & 1);
;                             u32x2 w0, w1; w0.x = cvtpk(v0[0], v0[1]); w0.y = cvtpk(v0[2], v0[3]); w1.x = cvtpk(v1[0], v1[1]); w1.y = cvtpk(v1[2], v1[3]);
;                             *(u32x2*)gb = w0; *(u32x2*)(gb + 8) = w1;
;                         } else store8(rowp + bj * HALF, acc[ai][bj][m][0] * cv[bj][0], acc[ai][bj][m][1] * cv[bj][1]); } }
.LBB0_473:
	s_mov_b64 s[48:49], -1
	s_and_b64 vcc, exec, s[6:7]
	v_pk_mul_f32 v[130:131], v[12:13], v[136:137]
	v_pk_mul_f32 v[128:129], v[8:9], v[138:139]
	s_cbranch_vccnz .LBB0_475
	v_pk_mul_f32 v[184:185], v[14:15], v[132:133]
	v_pk_mul_f32 v[186:187], v[10:11], v[134:135]
	v_cvt_pk_bf16_f32 v182, v130, v131
	v_cvt_pk_bf16_f32 v183, v184, v185
	v_cvt_pk_bf16_f32 v184, v128, v129
	v_cvt_pk_bf16_f32 v185, v186, v187
	s_mov_b64 s[48:49], 0
	global_store_dwordx4 v[174:175], v[182:185], off offset:256
.LBB0_475:
	s_andn2_b64 vcc, exec, s[48:49]
	s_cbranch_vccnz .LBB0_477
	v_pk_mul_f32 v[174:175], v[14:15], v[132:133]
	v_pk_mul_f32 v[182:183], v[10:11], v[134:135]
	v_cvt_pk_bf16_f32 v130, v130, v131
	v_cvt_pk_bf16_f32 v131, v174, v175
	v_cvt_pk_bf16_f32 v128, v128, v129
	v_cvt_pk_bf16_f32 v129, v182, v183
	global_store_dwordx2 v[178:179], v[130:131], off offset:256
	global_store_dwordx2 v[178:179], v[128:129], off offset:272
.LBB0_477:
	v_add_u32_e32 v128, 0xb0, v164
	v_mad_i64_i32 v[128:129], s[48:49], s82, v128, 0
	v_lshl_add_u64 v[128:129], v[128:129], 1, s[84:85]
	v_lshl_add_u64 v[128:129], s[38:39], 1, v[128:129]
	v_lshl_add_u64 v[174:175], v[148:149], 1, v[128:129]
	v_pk_mul_f32 v[130:131], v[22:23], v[172:173]
	v_pk_mul_f32 v[128:129], v[20:21], v[170:171]
	v_pk_mul_f32 v[168:169], v[18:19], v[168:169]
	v_pk_mul_f32 v[166:167], v[16:17], v[166:167]
	v_cvt_pk_bf16_f32 v128, v128, v129
	v_cvt_pk_bf16_f32 v129, v130, v131
	v_cvt_pk_bf16_f32 v130, v166, v167
	v_cvt_pk_bf16_f32 v131, v168, v169
	s_and_b64 vcc, exec, s[6:7]
	s_mov_b64 s[38:39], -1
	s_cbranch_vccnz .LBB0_479
	s_mov_b64 s[38:39], 0
	global_store_dwordx4 v[174:175], v[128:131], off
.LBB0_479:
	v_lshl_add_u64 v[166:167], v[150:151], 1, v[174:175]
	s_andn2_b64 vcc, exec, s[38:39]
	v_lshl_add_u64 v[166:167], v[166:167], 0, v[176:177]
	s_cbranch_vccnz .LBB0_481
	global_store_dwordx2 v[166:167], v[128:129], off
	global_store_dwordx2 v[166:167], v[130:131], off offset:16
.LBB0_481:
	s_mov_b64 s[38:39], -1
	s_and_b64 vcc, exec, s[6:7]
	v_pk_mul_f32 v[130:131], v[4:5], v[136:137]
	v_pk_mul_f32 v[128:129], v[0:1], v[138:139]
	s_cbranch_vccnz .LBB0_483
	v_pk_mul_f32 v[138:139], v[6:7], v[132:133]
	v_pk_mul_f32 v[168:169], v[2:3], v[134:135]
	v_cvt_pk_bf16_f32 v136, v130, v131
	v_cvt_pk_bf16_f32 v137, v138, v139
	v_cvt_pk_bf16_f32 v138, v128, v129
	v_cvt_pk_bf16_f32 v139, v168, v169
	s_mov_b64 s[38:39], 0
	global_store_dwordx4 v[174:175], v[136:139], off offset:256
.LBB0_483:
	s_andn2_b64 vcc, exec, s[38:39]
	s_cbranch_vccnz .LBB0_485
	v_pk_mul_f32 v[132:133], v[6:7], v[132:133]
	v_pk_mul_f32 v[134:135], v[2:3], v[134:135]
	v_cvt_pk_bf16_f32 v130, v130, v131
	v_cvt_pk_bf16_f32 v131, v132, v133
	v_cvt_pk_bf16_f32 v128, v128, v129
	v_cvt_pk_bf16_f32 v129, v134, v135
	global_store_dwordx2 v[166:167], v[130:131], off offset:256
	global_store_dwordx2 v[166:167], v[128:129], off offset:272

; __device__ __forceinline__ float sigm_f(float v) { return __builtin_amdgcn_rcpf(1.0f + __builtin_amdgcn_exp2f(-1.44269504f * v)); }
; __device__ __forceinline__ float silu_f(float v) { return v * sigm_f(v); }
;     __device__ __forceinline__ void operator()(const f32x4 (&acc)[2][2][4][2], const Unit& u, int wr, int wc, int fr, int fq) const {
;     ...
; #pragma unroll
;                 for (int ai = 0; ai < 2; ++ai)
; #pragma unroll
;                     for (int m = 0; m < 4; ++m) { const int row = row0 + ai * HALF + m * 16; const float rsv = __builtin_amdgcn_rsqf(rs[row] * (1.0f / 1024.0f) + 1e-6f);
;                         bf16_t* rowp = O + (size_t)row * ldc + u.pn * BM + cw;
; #pragma unroll
;                         for (int bj = 0; bj < 2; ++bj) { f32x4 v0 = acc[ai][bj][m][0] * rsv, v1 = acc[ai][bj][m][1] * rsv;
;                             if (sub == 1) {
; #pragma unroll
;                                 for (int e = 0; e < 4; ++e) { v0[e] = silu_f(v0[e]); v1[e] = silu_f(v1[e]); } }
;                             else if (sub == 3) {
; #pragma unroll
;                                 for (int e = 0; e < 4; ++e) { v0[e] = sigm_f(v0[e]); v1[e] = sigm_f(v1[e]); } }
;                             store8(rowp + bj * HALF, v0, v1); } }
.LBB0_494:
	v_mad_i64_i32 v[132:133], s[6:7], s82, v164, 0
	v_lshl_add_u64 v[132:133], v[132:133], 1, s[84:85]
	v_lshl_add_u64 v[132:133], s[62:63], 1, v[132:133]
	v_lshl_add_u64 v[132:133], v[148:149], 1, v[132:133]
	v_cvt_pk_bf16_f32 v134, v165, v167
	v_cvt_pk_bf16_f32 v135, v169, v172
	v_cvt_pk_bf16_f32 v136, v166, v168
	v_cvt_pk_bf16_f32 v137, v170, v171
	v_mov_b32_e32 v131, v130
	v_mov_b32_e32 v138, v130
	v_mov_b32_e32 v139, v130
	global_store_dwordx4 v[132:133], v[134:137], off
	v_pk_mul_f32 v[166:167], v[104:105], v[130:131]
	s_cmp_gt_i32 s38, 2
	v_pk_mul_f32 v[134:135], v[110:111], v[138:139]
	v_pk_mul_f32 v[136:137], v[108:109], v[130:131]
	v_pk_mul_f32 v[138:139], v[106:107], v[138:139]
	s_mov_b64 s[6:7], -1
	s_cbranch_scc0 .LBB0_496
	v_mul_f32_e32 v172, 0xbfb8aa3b, v135
	v_mul_f32_e32 v131, 0xbfb8aa3b, v136
	v_mul_f32_e32 v165, 0xbfb8aa3b, v166
	v_mul_f32_e32 v168, 0xbfb8aa3b, v137
	v_mul_f32_e32 v169, 0xbfb8aa3b, v167
	v_mul_f32_e32 v170, 0xbfb8aa3b, v134
	v_mul_f32_e32 v171, 0xbfb8aa3b, v138
	v_exp_f32_e32 v172, v172
	v_mul_f32_e32 v173, 0xbfb8aa3b, v139
	v_exp_f32_e32 v131, v131
	v_exp_f32_e32 v165, v165
	v_exp_f32_e32 v168, v168
	v_exp_f32_e32 v169, v169
	v_exp_f32_e32 v170, v170
	v_exp_f32_e32 v171, v171
	v_exp_f32_e32 v174, v173
	v_add_f32_e32 v172, 1.0, v172
	v_add_f32_e32 v131, 1.0, v131
	v_add_f32_e32 v165, 1.0, v165
	v_add_f32_e32 v168, 1.0, v168
	v_add_f32_e32 v169, 1.0, v169
	v_add_f32_e32 v170, 1.0, v170
	v_add_f32_e32 v171, 1.0, v171
	v_rcp_f32_e32 v173, v172
	v_add_f32_e32 v172, 1.0, v174
	v_rcp_f32_e32 v131, v131
	v_rcp_f32_e32 v165, v165
	v_rcp_f32_e32 v168, v168
	v_rcp_f32_e32 v169, v169
	v_rcp_f32_e32 v170, v170
	v_rcp_f32_e32 v171, v171
	v_rcp_f32_e32 v172, v172
	s_mov_b64 s[6:7], 0

; __device__ __forceinline__ float sigm_f(float v) { return __builtin_amdgcn_rcpf(1.0f + __builtin_amdgcn_exp2f(-1.44269504f * v)); }
; __device__ __forceinline__ float silu_f(float v) { return v * sigm_f(v); }
;     __device__ __forceinline__ void operator()(const f32x4 (&acc)[2][2][4][2], const Unit& u, int wr, int wc, int fr, int fq) const {
;     ...
; #pragma unroll
;                 for (int ai = 0; ai < 2; ++ai)
; #pragma unroll
;                     for (int m = 0; m < 4; ++m) { const int row = row0 + ai * HALF + m * 16; const float rsv = __builtin_amdgcn_rsqf(rs[row] * (1.0f / 1024.0f) + 1e-6f);
;                         bf16_t* rowp = O + (size_t)row * ldc + u.pn * BM + cw;
; #pragma unroll
;                         for (int bj = 0; bj < 2; ++bj) { f32x4 v0 = acc[ai][bj][m][0] * rsv, v1 = acc[ai][bj][m][1] * rsv;
;                             if (sub == 1) {
; #pragma unroll
;                                 for (int e = 0; e < 4; ++e) { v0[e] = silu_f(v0[e]); v1[e] = silu_f(v1[e]); } }
;                             else if (sub == 3) {
; #pragma unroll
;                                 for (int e = 0; e < 4; ++e) { v0[e] = sigm_f(v0[e]); v1[e] = sigm_f(v1[e]); } }
;                             store8(rowp + bj * HALF, v0, v1); } }
.LBB0_500:
	v_cvt_pk_bf16_f32 v134, v131, v168
	v_cvt_pk_bf16_f32 v135, v170, v173
	v_cvt_pk_bf16_f32 v136, v165, v169
	v_cvt_pk_bf16_f32 v137, v171, v172
	global_store_dwordx4 v[132:133], v[134:137], off offset:256
	s_cmp_gt_i32 s38, 2
	s_mov_b64 s[6:7], -1
	v_fmamk_f32 v131, v247, 0x3a800000, v237
	v_rsq_f32_e32 v132, v131
	s_nop 0
	v_pk_mul_f32 v[136:137], v[118:119], v[132:133] op_sel_hi:[1,0]
	v_pk_mul_f32 v[166:167], v[116:117], v[132:133] op_sel_hi:[1,0]
	v_pk_mul_f32 v[134:135], v[114:115], v[132:133] op_sel_hi:[1,0]
	v_pk_mul_f32 v[138:139], v[112:113], v[132:133] op_sel_hi:[1,0]
	s_cbranch_scc0 .LBB0_502
	v_mul_f32_e32 v133, 0xbfb8aa3b, v138
	v_exp_f32_e32 v133, v133
	v_mul_f32_e32 v165, 0xbfb8aa3b, v167
	v_exp_f32_e32 v168, v165
	v_mul_f32_e32 v165, 0xbfb8aa3b, v139
	v_exp_f32_e32 v169, v165
	v_add_f32_e32 v133, 1.0, v133
	v_rcp_f32_e32 v165, v133
	v_add_f32_e32 v133, 1.0, v168
	v_rcp_f32_e32 v168, v133
	v_add_f32_e32 v133, 1.0, v169
	v_mul_f32_e32 v169, 0xbfb8aa3b, v136
	v_exp_f32_e32 v170, v169
	v_mul_f32_e32 v169, 0xbfb8aa3b, v134
	v_exp_f32_e32 v171, v169
	v_rcp_f32_e32 v169, v133
	v_add_f32_e32 v133, 1.0, v170
	v_rcp_f32_e32 v170, v133
	v_add_f32_e32 v133, 1.0, v171
	v_mul_f32_e32 v171, 0xbfb8aa3b, v137
	v_mul_f32_e32 v131, 0xbfb8aa3b, v166
	v_exp_f32_e32 v172, v171
	v_mul_f32_e32 v171, 0xbfb8aa3b, v135
	v_exp_f32_e32 v131, v131
	v_exp_f32_e32 v174, v171
	v_rcp_f32_e32 v171, v133
	v_add_f32_e32 v133, 1.0, v172
	v_add_f32_e32 v131, 1.0, v131
	v_rcp_f32_e32 v173, v133
	v_add_f32_e32 v133, 1.0, v174
	v_rcp_f32_e32 v131, v131
	v_rcp_f32_e32 v172, v133
	s_mov_b64 s[6:7], 0

; __device__ __forceinline__ float sigm_f(float v) { return __builtin_amdgcn_rcpf(1.0f + __builtin_amdgcn_exp2f(-1.44269504f * v)); }
; __device__ __forceinline__ float silu_f(float v) { return v * sigm_f(v); }
;     __device__ __forceinline__ void operator()(const f32x4 (&acc)[2][2][4][2], const Unit& u, int wr, int wc, int fr, int fq) const {
;     ...
; #pragma unroll
;                 for (int ai = 0; ai < 2; ++ai)
; #pragma unroll
;                     for (int m = 0; m < 4; ++m) { const int row = row0 + ai * HALF + m * 16; const float rsv = __builtin_amdgcn_rsqf(rs[row] * (1.0f / 1024.0f) + 1e-6f);
;                         bf16_t* rowp = O + (size_t)row * ldc + u.pn * BM + cw;
; #pragma unroll
;                         for (int bj = 0; bj < 2; ++bj) { f32x4 v0 = acc[ai][bj][m][0] * rsv, v1 = acc[ai][bj][m][1] * rsv;
;                             if (sub == 1) {
; #pragma unroll
;                                 for (int e = 0; e < 4; ++e) { v0[e] = silu_f(v0[e]); v1[e] = silu_f(v1[e]); } }
;                             else if (sub == 3) {
; #pragma unroll
;                                 for (int e = 0; e < 4; ++e) { v0[e] = sigm_f(v0[e]); v1[e] = sigm_f(v1[e]); } }
;                             store8(rowp + bj * HALF, v0, v1); } }
.LBB0_506:
	v_or_b32_e32 v134, 16, v164
	v_mad_i64_i32 v[134:135], s[6:7], s82, v134, 0
	v_lshl_add_u64 v[134:135], v[134:135], 1, s[84:85]
	v_lshl_add_u64 v[134:135], s[62:63], 1, v[134:135]
	v_lshl_add_u64 v[134:135], v[148:149], 1, v[134:135]
	v_cvt_pk_bf16_f32 v136, v131, v168
	v_cvt_pk_bf16_f32 v137, v170, v173
	v_cvt_pk_bf16_f32 v138, v165, v169
	v_cvt_pk_bf16_f32 v139, v171, v172
	v_mov_b32_e32 v133, v132
	v_mov_b32_e32 v166, v132
	v_mov_b32_e32 v167, v132
	global_store_dwordx4 v[134:135], v[136:139], off
	s_cmp_gt_i32 s38, 2
	s_mov_b64 s[6:7], -1
	v_pk_mul_f32 v[136:137], v[94:95], v[166:167]
	v_pk_mul_f32 v[138:139], v[92:93], v[132:133]
	v_pk_mul_f32 v[166:167], v[90:91], v[166:167]
	v_pk_mul_f32 v[132:133], v[88:89], v[132:133]
	s_cbranch_scc0 .LBB0_508
	v_mul_f32_e32 v172, 0xbfb8aa3b, v137
	v_mul_f32_e32 v131, 0xbfb8aa3b, v138
	v_mul_f32_e32 v165, 0xbfb8aa3b, v132
	v_mul_f32_e32 v168, 0xbfb8aa3b, v139
	v_mul_f32_e32 v169, 0xbfb8aa3b, v133
	v_mul_f32_e32 v170, 0xbfb8aa3b, v136
	v_mul_f32_e32 v171, 0xbfb8aa3b, v166
	v_exp_f32_e32 v172, v172
	v_mul_f32_e32 v173, 0xbfb8aa3b, v167
	v_exp_f32_e32 v131, v131
	v_exp_f32_e32 v165, v165
	v_exp_f32_e32 v168, v168
	v_exp_f32_e32 v169, v169
	v_exp_f32_e32 v170, v170
	v_exp_f32_e32 v171, v171
	v_exp_f32_e32 v174, v173
	v_add_f32_e32 v172, 1.0, v172
	v_add_f32_e32 v131, 1.0, v131
	v_add_f32_e32 v165, 1.0, v165
	v_add_f32_e32 v168, 1.0, v168
	v_add_f32_e32 v169, 1.0, v169
	v_add_f32_e32 v170, 1.0, v170
	v_add_f32_e32 v171, 1.0, v171
	v_rcp_f32_e32 v173, v172
	v_add_f32_e32 v172, 1.0, v174
	v_rcp_f32_e32 v131, v131
	v_rcp_f32_e32 v165, v165
	v_rcp_f32_e32 v168, v168
	v_rcp_f32_e32 v169, v169
	v_rcp_f32_e32 v170, v170
	v_rcp_f32_e32 v171, v171
	v_rcp_f32_e32 v172, v172
	s_mov_b64 s[6:7], 0

; __device__ __forceinline__ float sigm_f(float v) { return __builtin_amdgcn_rcpf(1.0f + __builtin_amdgcn_exp2f(-1.44269504f * v)); }
; __device__ __forceinline__ float silu_f(float v) { return v * sigm_f(v); }
;     __device__ __forceinline__ void operator()(const f32x4 (&acc)[2][2][4][2], const Unit& u, int wr, int wc, int fr, int fq) const {
;     ...
; #pragma unroll
;                 for (int ai = 0; ai < 2; ++ai)
; #pragma unroll
;                     for (int m = 0; m < 4; ++m) { const int row = row0 + ai * HALF + m * 16; const float rsv = __builtin_amdgcn_rsqf(rs[row] * (1.0f / 1024.0f) + 1e-6f);
;                         bf16_t* rowp = O + (size_t)row * ldc + u.pn * BM + cw;
; #pragma unroll
;                         for (int bj = 0; bj < 2; ++bj) { f32x4 v0 = acc[ai][bj][m][0] * rsv, v1 = acc[ai][bj][m][1] * rsv;
;                             if (sub == 1) {
; #pragma unroll
;                                 for (int e = 0; e < 4; ++e) { v0[e] = silu_f(v0[e]); v1[e] = silu_f(v1[e]); } }
;                             else if (sub == 3) {
; #pragma unroll
;                                 for (int e = 0; e < 4; ++e) { v0[e] = sigm_f(v0[e]); v1[e] = sigm_f(v1[e]); } }
;                             store8(rowp + bj * HALF, v0, v1); } }
.LBB0_512:
	v_cvt_pk_bf16_f32 v136, v131, v168
	v_cvt_pk_bf16_f32 v137, v170, v173
	v_cvt_pk_bf16_f32 v138, v165, v169
	v_cvt_pk_bf16_f32 v139, v171, v172
	global_store_dwordx4 v[134:135], v[136:139], off offset:256
	s_cmp_gt_i32 s38, 2
	s_mov_b64 s[6:7], -1
	v_fmamk_f32 v131, v248, 0x3a800000, v237
	v_rsq_f32_e32 v132, v131
	s_nop 0
	v_pk_mul_f32 v[136:137], v[102:103], v[132:133] op_sel_hi:[1,0]
	v_pk_mul_f32 v[166:167], v[100:101], v[132:133] op_sel_hi:[1,0]
	v_pk_mul_f32 v[134:135], v[98:99], v[132:133] op_sel_hi:[1,0]
	v_pk_mul_f32 v[138:139], v[96:97], v[132:133] op_sel_hi:[1,0]
	s_cbranch_scc0 .LBB0_514
	v_mul_f32_e32 v133, 0xbfb8aa3b, v138
	v_exp_f32_e32 v133, v133
	v_mul_f32_e32 v165, 0xbfb8aa3b, v167
	v_exp_f32_e32 v168, v165
	v_mul_f32_e32 v165, 0xbfb8aa3b, v139
	v_exp_f32_e32 v169, v165
	v_add_f32_e32 v133, 1.0, v133
	v_rcp_f32_e32 v165, v133
	v_add_f32_e32 v133, 1.0, v168
	v_rcp_f32_e32 v168, v133
	v_add_f32_e32 v133, 1.0, v169
	v_mul_f32_e32 v169, 0xbfb8aa3b, v136
	v_exp_f32_e32 v170, v169
	v_mul_f32_e32 v169, 0xbfb8aa3b, v134
	v_exp_f32_e32 v171, v169
	v_rcp_f32_e32 v169, v133
	v_add_f32_e32 v133, 1.0, v170
	v_rcp_f32_e32 v170, v133
	v_add_f32_e32 v133, 1.0, v171
	v_mul_f32_e32 v171, 0xbfb8aa3b, v137
	v_mul_f32_e32 v131, 0xbfb8aa3b, v166
	v_exp_f32_e32 v172, v171
	v_mul_f32_e32 v171, 0xbfb8aa3b, v135
	v_exp_f32_e32 v131, v131
	v_exp_f32_e32 v174, v171
	v_rcp_f32_e32 v171, v133
	v_add_f32_e32 v133, 1.0, v172
	v_add_f32_e32 v131, 1.0, v131
	v_rcp_f32_e32 v173, v133
	v_add_f32_e32 v133, 1.0, v174
	v_rcp_f32_e32 v131, v131
	v_rcp_f32_e32 v172, v133
	s_mov_b64 s[6:7], 0

; __device__ __forceinline__ float sigm_f(float v) { return __builtin_amdgcn_rcpf(1.0f + __builtin_amdgcn_exp2f(-1.44269504f * v)); }
; __device__ __forceinline__ float silu_f(float v) { return v * sigm_f(v); }
;     __device__ __forceinline__ void operator()(const f32x4 (&acc)[2][2][4][2], const Unit& u, int wr, int wc, int fr, int fq) const {
;     ...
; #pragma unroll
;                 for (int ai = 0; ai < 2; ++ai)
; #pragma unroll
;                     for (int m = 0; m < 4; ++m) { const int row = row0 + ai * HALF + m * 16; const float rsv = __builtin_amdgcn_rsqf(rs[row] * (1.0f / 1024.0f) + 1e-6f);
;                         bf16_t* rowp = O + (size_t)row * ldc + u.pn * BM + cw;
; #pragma unroll
;                         for (int bj = 0; bj < 2; ++bj) { f32x4 v0 = acc[ai][bj][m][0] * rsv, v1 = acc[ai][bj][m][1] * rsv;
;                             if (sub == 1) {
; #pragma unroll
;                                 for (int e = 0; e < 4; ++e) { v0[e] = silu_f(v0[e]); v1[e] = silu_f(v1[e]); } }
;                             else if (sub == 3) {
; #pragma unroll
;                                 for (int e = 0; e < 4; ++e) { v0[e] = sigm_f(v0[e]); v1[e] = sigm_f(v1[e]); } }
;                             store8(rowp + bj * HALF, v0, v1); } }
.LBB0_518:
	v_or_b32_e32 v134, 32, v164
	v_mad_i64_i32 v[134:135], s[6:7], s82, v134, 0
	v_lshl_add_u64 v[134:135], v[134:135], 1, s[84:85]
	v_lshl_add_u64 v[134:135], s[62:63], 1, v[134:135]
	v_lshl_add_u64 v[134:135], v[148:149], 1, v[134:135]
	v_cvt_pk_bf16_f32 v136, v131, v168
	v_cvt_pk_bf16_f32 v137, v170, v173
	v_cvt_pk_bf16_f32 v138, v165, v169
	v_cvt_pk_bf16_f32 v139, v171, v172
	v_mov_b32_e32 v133, v132
	v_mov_b32_e32 v166, v132
	v_mov_b32_e32 v167, v132
	global_store_dwordx4 v[134:135], v[136:139], off
	s_cmp_gt_i32 s38, 2
	s_mov_b64 s[6:7], -1
	v_pk_mul_f32 v[136:137], v[78:79], v[166:167]
	v_pk_mul_f32 v[138:139], v[76:77], v[132:133]
	v_pk_mul_f32 v[166:167], v[74:75], v[166:167]
	v_pk_mul_f32 v[132:133], v[72:73], v[132:133]
	s_cbranch_scc0 .LBB0_520
	v_mul_f32_e32 v172, 0xbfb8aa3b, v137
	v_mul_f32_e32 v131, 0xbfb8aa3b, v138
	v_mul_f32_e32 v165, 0xbfb8aa3b, v132
	v_mul_f32_e32 v168, 0xbfb8aa3b, v139
	v_mul_f32_e32 v169, 0xbfb8aa3b, v133
	v_mul_f32_e32 v170, 0xbfb8aa3b, v136
	v_mul_f32_e32 v171, 0xbfb8aa3b, v166
	v_exp_f32_e32 v172, v172
	v_mul_f32_e32 v173, 0xbfb8aa3b, v167
	v_exp_f32_e32 v131, v131
	v_exp_f32_e32 v165, v165
	v_exp_f32_e32 v168, v168
	v_exp_f32_e32 v169, v169
	v_exp_f32_e32 v170, v170
	v_exp_f32_e32 v171, v171
	v_exp_f32_e32 v174, v173
	v_add_f32_e32 v172, 1.0, v172
	v_add_f32_e32 v131, 1.0, v131
	v_add_f32_e32 v165, 1.0, v165
	v_add_f32_e32 v168, 1.0, v168
	v_add_f32_e32 v169, 1.0, v169
	v_add_f32_e32 v170, 1.0, v170
	v_add_f32_e32 v171, 1.0, v171
	v_rcp_f32_e32 v173, v172
	v_add_f32_e32 v172, 1.0, v174
	v_rcp_f32_e32 v131, v131
	v_rcp_f32_e32 v165, v165
	v_rcp_f32_e32 v168, v168
	v_rcp_f32_e32 v169, v169
	v_rcp_f32_e32 v170, v170
	v_rcp_f32_e32 v171, v171
	v_rcp_f32_e32 v172, v172
	s_mov_b64 s[6:7], 0

; __device__ __forceinline__ float sigm_f(float v) { return __builtin_amdgcn_rcpf(1.0f + __builtin_amdgcn_exp2f(-1.44269504f * v)); }
; __device__ __forceinline__ float silu_f(float v) { return v * sigm_f(v); }
;     __device__ __forceinline__ void operator()(const f32x4 (&acc)[2][2][4][2], const Unit& u, int wr, int wc, int fr, int fq) const {
;     ...
; #pragma unroll
;                 for (int ai = 0; ai < 2; ++ai)
; #pragma unroll
;                     for (int m = 0; m < 4; ++m) { const int row = row0 + ai * HALF + m * 16; const float rsv = __builtin_amdgcn_rsqf(rs[row] * (1.0f / 1024.0f) + 1e-6f);
;                         bf16_t* rowp = O + (size_t)row * ldc + u.pn * BM + cw;
; #pragma unroll
;                         for (int bj = 0; bj < 2; ++bj) { f32x4 v0 = acc[ai][bj][m][0] * rsv, v1 = acc[ai][bj][m][1] * rsv;
;                             if (sub == 1) {
; #pragma unroll
;                                 for (int e = 0; e < 4; ++e) { v0[e] = silu_f(v0[e]); v1[e] = silu_f(v1[e]); } }
;                             else if (sub == 3) {
; #pragma unroll
;                                 for (int e = 0; e < 4; ++e) { v0[e] = sigm_f(v0[e]); v1[e] = sigm_f(v1[e]); } }
;                             store8(rowp + bj * HALF, v0, v1); } }
.LBB0_524:
	v_cvt_pk_bf16_f32 v136, v131, v168
	v_cvt_pk_bf16_f32 v137, v170, v173
	v_cvt_pk_bf16_f32 v138, v165, v169
	v_cvt_pk_bf16_f32 v139, v171, v172
	global_store_dwordx4 v[134:135], v[136:139], off offset:256
	s_cmp_gt_i32 s38, 2
	s_mov_b64 s[6:7], -1
	v_fmamk_f32 v131, v249, 0x3a800000, v237
	v_rsq_f32_e32 v132, v131
	s_nop 0
	v_pk_mul_f32 v[136:137], v[86:87], v[132:133] op_sel_hi:[1,0]
	v_pk_mul_f32 v[166:167], v[84:85], v[132:133] op_sel_hi:[1,0]
	v_pk_mul_f32 v[134:135], v[82:83], v[132:133] op_sel_hi:[1,0]
	v_pk_mul_f32 v[138:139], v[80:81], v[132:133] op_sel_hi:[1,0]
	s_cbranch_scc0 .LBB0_526
	v_mul_f32_e32 v133, 0xbfb8aa3b, v138
	v_exp_f32_e32 v133, v133
	v_mul_f32_e32 v165, 0xbfb8aa3b, v167
	v_exp_f32_e32 v168, v165
	v_mul_f32_e32 v165, 0xbfb8aa3b, v139
	v_exp_f32_e32 v169, v165
	v_add_f32_e32 v133, 1.0, v133
	v_rcp_f32_e32 v165, v133
	v_add_f32_e32 v133, 1.0, v168
	v_rcp_f32_e32 v168, v133
	v_add_f32_e32 v133, 1.0, v169
	v_mul_f32_e32 v169, 0xbfb8aa3b, v136
	v_exp_f32_e32 v170, v169
	v_mul_f32_e32 v169, 0xbfb8aa3b, v134
	v_exp_f32_e32 v171, v169
	v_rcp_f32_e32 v169, v133
	v_add_f32_e32 v133, 1.0, v170
	v_rcp_f32_e32 v170, v133
	v_add_f32_e32 v133, 1.0, v171
	v_mul_f32_e32 v171, 0xbfb8aa3b, v137
	v_mul_f32_e32 v131, 0xbfb8aa3b, v166
	v_exp_f32_e32 v172, v171
	v_mul_f32_e32 v171, 0xbfb8aa3b, v135
	v_exp_f32_e32 v131, v131
	v_exp_f32_e32 v174, v171
	v_rcp_f32_e32 v171, v133
	v_add_f32_e32 v133, 1.0, v172
	v_add_f32_e32 v131, 1.0, v131
	v_rcp_f32_e32 v173, v133
	v_add_f32_e32 v133, 1.0, v174
	v_rcp_f32_e32 v131, v131
	v_rcp_f32_e32 v172, v133
	s_mov_b64 s[6:7], 0

; __device__ __forceinline__ float sigm_f(float v) { return __builtin_amdgcn_rcpf(1.0f + __builtin_amdgcn_exp2f(-1.44269504f * v)); }
; __device__ __forceinline__ float silu_f(float v) { return v * sigm_f(v); }
;     __device__ __forceinline__ void operator()(const f32x4 (&acc)[2][2][4][2], const Unit& u, int wr, int wc, int fr, int fq) const {
;     ...
; #pragma unroll
;                 for (int ai = 0; ai < 2; ++ai)
; #pragma unroll
;                     for (int m = 0; m < 4; ++m) { const int row = row0 + ai * HALF + m * 16; const float rsv = __builtin_amdgcn_rsqf(rs[row] * (1.0f / 1024.0f) + 1e-6f);
;                         bf16_t* rowp = O + (size_t)row * ldc + u.pn * BM + cw;
; #pragma unroll
;                         for (int bj = 0; bj < 2; ++bj) { f32x4 v0 = acc[ai][bj][m][0] * rsv, v1 = acc[ai][bj][m][1] * rsv;
;                             if (sub == 1) {
; #pragma unroll
;                                 for (int e = 0; e < 4; ++e) { v0[e] = silu_f(v0[e]); v1[e] = silu_f(v1[e]); } }
;                             else if (sub == 3) {
; #pragma unroll
;                                 for (int e = 0; e < 4; ++e) { v0[e] = sigm_f(v0[e]); v1[e] = sigm_f(v1[e]); } }
;                             store8(rowp + bj * HALF, v0, v1); } }
.LBB0_530:
	v_or_b32_e32 v134, 48, v164
	v_mad_i64_i32 v[134:135], s[6:7], s82, v134, 0
	v_lshl_add_u64 v[134:135], v[134:135], 1, s[84:85]
	v_lshl_add_u64 v[134:135], s[62:63], 1, v[134:135]
	v_lshl_add_u64 v[134:135], v[148:149], 1, v[134:135]
	v_cvt_pk_bf16_f32 v136, v131, v168
	v_cvt_pk_bf16_f32 v137, v170, v173
	v_cvt_pk_bf16_f32 v138, v165, v169
	v_cvt_pk_bf16_f32 v139, v171, v172
	v_mov_b32_e32 v133, v132
	v_mov_b32_e32 v166, v132
	v_mov_b32_e32 v167, v132
	global_store_dwordx4 v[134:135], v[136:139], off
	s_cmp_gt_i32 s38, 2
	s_mov_b64 s[6:7], -1
	v_pk_mul_f32 v[136:137], v[70:71], v[166:167]
	v_pk_mul_f32 v[138:139], v[68:69], v[132:133]
	v_pk_mul_f32 v[166:167], v[66:67], v[166:167]
	v_pk_mul_f32 v[132:133], v[64:65], v[132:133]
	s_cbranch_scc0 .LBB0_532
	v_mul_f32_e32 v172, 0xbfb8aa3b, v137
	v_mul_f32_e32 v131, 0xbfb8aa3b, v138
	v_mul_f32_e32 v165, 0xbfb8aa3b, v132
	v_mul_f32_e32 v168, 0xbfb8aa3b, v139
	v_mul_f32_e32 v169, 0xbfb8aa3b, v133
	v_mul_f32_e32 v170, 0xbfb8aa3b, v136
	v_mul_f32_e32 v171, 0xbfb8aa3b, v166
	v_exp_f32_e32 v172, v172
	v_mul_f32_e32 v173, 0xbfb8aa3b, v167
	v_exp_f32_e32 v131, v131
	v_exp_f32_e32 v165, v165
	v_exp_f32_e32 v168, v168
	v_exp_f32_e32 v169, v169
	v_exp_f32_e32 v170, v170
	v_exp_f32_e32 v171, v171
	v_exp_f32_e32 v174, v173
	v_add_f32_e32 v172, 1.0, v172
	v_add_f32_e32 v131, 1.0, v131
	v_add_f32_e32 v165, 1.0, v165
	v_add_f32_e32 v168, 1.0, v168
	v_add_f32_e32 v169, 1.0, v169
	v_add_f32_e32 v170, 1.0, v170
	v_add_f32_e32 v171, 1.0, v171
	v_rcp_f32_e32 v173, v172
	v_add_f32_e32 v172, 1.0, v174
	v_rcp_f32_e32 v131, v131
	v_rcp_f32_e32 v165, v165
	v_rcp_f32_e32 v168, v168
	v_rcp_f32_e32 v169, v169
	v_rcp_f32_e32 v170, v170
	v_rcp_f32_e32 v171, v171
	v_rcp_f32_e32 v172, v172
	s_mov_b64 s[6:7], 0

; __device__ __forceinline__ float sigm_f(float v) { return __builtin_amdgcn_rcpf(1.0f + __builtin_amdgcn_exp2f(-1.44269504f * v)); }
; __device__ __forceinline__ float silu_f(float v) { return v * sigm_f(v); }
;     __device__ __forceinline__ void operator()(const f32x4 (&acc)[2][2][4][2], const Unit& u, int wr, int wc, int fr, int fq) const {
;     ...
; #pragma unroll
;                 for (int ai = 0; ai < 2; ++ai)
; #pragma unroll
;                     for (int m = 0; m < 4; ++m) { const int row = row0 + ai * HALF + m * 16; const float rsv = __builtin_amdgcn_rsqf(rs[row] * (1.0f / 1024.0f) + 1e-6f);
;                         bf16_t* rowp = O + (size_t)row * ldc + u.pn * BM + cw;
; #pragma unroll
;                         for (int bj = 0; bj < 2; ++bj) { f32x4 v0 = acc[ai][bj][m][0] * rsv, v1 = acc[ai][bj][m][1] * rsv;
;                             if (sub == 1) {
; #pragma unroll
;                                 for (int e = 0; e < 4; ++e) { v0[e] = silu_f(v0[e]); v1[e] = silu_f(v1[e]); } }
;                             else if (sub == 3) {
; #pragma unroll
;                                 for (int e = 0; e < 4; ++e) { v0[e] = sigm_f(v0[e]); v1[e] = sigm_f(v1[e]); } }
;                             store8(rowp + bj * HALF, v0, v1); } }
.LBB0_536:
	v_cvt_pk_bf16_f32 v136, v131, v168
	v_cvt_pk_bf16_f32 v137, v170, v173
	v_cvt_pk_bf16_f32 v138, v165, v169
	v_cvt_pk_bf16_f32 v139, v171, v172
	global_store_dwordx4 v[134:135], v[136:139], off offset:256
	s_cmp_gt_i32 s38, 2
	s_mov_b64 s[6:7], -1
	v_fmamk_f32 v131, v250, 0x3a800000, v237
	v_rsq_f32_e32 v132, v131
	s_nop 0
	v_pk_mul_f32 v[136:137], v[62:63], v[132:133] op_sel_hi:[1,0]
	v_pk_mul_f32 v[166:167], v[60:61], v[132:133] op_sel_hi:[1,0]
	v_pk_mul_f32 v[134:135], v[58:59], v[132:133] op_sel_hi:[1,0]
	v_pk_mul_f32 v[138:139], v[56:57], v[132:133] op_sel_hi:[1,0]
	s_cbranch_scc0 .LBB0_538
	v_mul_f32_e32 v133, 0xbfb8aa3b, v138
	v_exp_f32_e32 v133, v133
	v_mul_f32_e32 v165, 0xbfb8aa3b, v167
	v_exp_f32_e32 v168, v165
	v_mul_f32_e32 v165, 0xbfb8aa3b, v139
	v_exp_f32_e32 v169, v165
	v_add_f32_e32 v133, 1.0, v133
	v_rcp_f32_e32 v165, v133
	v_add_f32_e32 v133, 1.0, v168
	v_rcp_f32_e32 v168, v133
	v_add_f32_e32 v133, 1.0, v169
	v_mul_f32_e32 v169, 0xbfb8aa3b, v136
	v_exp_f32_e32 v170, v169
	v_mul_f32_e32 v169, 0xbfb8aa3b, v134
	v_exp_f32_e32 v171, v169
	v_rcp_f32_e32 v169, v133
	v_add_f32_e32 v133, 1.0, v170
	v_rcp_f32_e32 v170, v133
	v_add_f32_e32 v133, 1.0, v171
	v_mul_f32_e32 v171, 0xbfb8aa3b, v137
	v_mul_f32_e32 v131, 0xbfb8aa3b, v166
	v_exp_f32_e32 v172, v171
	v_mul_f32_e32 v171, 0xbfb8aa3b, v135
	v_exp_f32_e32 v131, v131
	v_exp_f32_e32 v174, v171
	v_rcp_f32_e32 v171, v133
	v_add_f32_e32 v133, 1.0, v172
	v_add_f32_e32 v131, 1.0, v131
	v_rcp_f32_e32 v173, v133
	v_add_f32_e32 v133, 1.0, v174
	v_rcp_f32_e32 v131, v131
	v_rcp_f32_e32 v172, v133
	s_mov_b64 s[6:7], 0

; __device__ __forceinline__ float sigm_f(float v) { return __builtin_amdgcn_rcpf(1.0f + __builtin_amdgcn_exp2f(-1.44269504f * v)); }
; __device__ __forceinline__ float silu_f(float v) { return v * sigm_f(v); }
;     __device__ __forceinline__ void operator()(const f32x4 (&acc)[2][2][4][2], const Unit& u, int wr, int wc, int fr, int fq) const {
;     ...
; #pragma unroll
;                 for (int ai = 0; ai < 2; ++ai)
; #pragma unroll
;                     for (int m = 0; m < 4; ++m) { const int row = row0 + ai * HALF + m * 16; const float rsv = __builtin_amdgcn_rsqf(rs[row] * (1.0f / 1024.0f) + 1e-6f);
;                         bf16_t* rowp = O + (size_t)row * ldc + u.pn * BM + cw;
; #pragma unroll
;                         for (int bj = 0; bj < 2; ++bj) { f32x4 v0 = acc[ai][bj][m][0] * rsv, v1 = acc[ai][bj][m][1] * rsv;
;                             if (sub == 1) {
; #pragma unroll
;                                 for (int e = 0; e < 4; ++e) { v0[e] = silu_f(v0[e]); v1[e] = silu_f(v1[e]); } }
;                             else if (sub == 3) {
; #pragma unroll
;                                 for (int e = 0; e < 4; ++e) { v0[e] = sigm_f(v0[e]); v1[e] = sigm_f(v1[e]); } }
;                             store8(rowp + bj * HALF, v0, v1); } }
.LBB0_542:
	v_add_u32_e32 v134, 0x80, v164
	v_mad_i64_i32 v[134:135], s[6:7], s82, v134, 0
	v_lshl_add_u64 v[134:135], v[134:135], 1, s[84:85]
	v_lshl_add_u64 v[134:135], s[62:63], 1, v[134:135]
	v_lshl_add_u64 v[134:135], v[148:149], 1, v[134:135]
	v_cvt_pk_bf16_f32 v136, v131, v168
	v_cvt_pk_bf16_f32 v137, v170, v173
	v_cvt_pk_bf16_f32 v138, v165, v169
	v_cvt_pk_bf16_f32 v139, v171, v172
	v_mov_b32_e32 v133, v132
	v_mov_b32_e32 v166, v132
	v_mov_b32_e32 v167, v132
	global_store_dwordx4 v[134:135], v[136:139], off
	s_cmp_gt_i32 s38, 2
	s_mov_b64 s[6:7], -1
	v_pk_mul_f32 v[136:137], v[46:47], v[166:167]
	v_pk_mul_f32 v[138:139], v[44:45], v[132:133]
	v_pk_mul_f32 v[166:167], v[42:43], v[166:167]
	v_pk_mul_f32 v[132:133], v[40:41], v[132:133]
	s_cbranch_scc0 .LBB0_544
	v_mul_f32_e32 v172, 0xbfb8aa3b, v137
	v_mul_f32_e32 v131, 0xbfb8aa3b, v138
	v_mul_f32_e32 v165, 0xbfb8aa3b, v132
	v_mul_f32_e32 v168, 0xbfb8aa3b, v139
	v_mul_f32_e32 v169, 0xbfb8aa3b, v133
	v_mul_f32_e32 v170, 0xbfb8aa3b, v136
	v_mul_f32_e32 v171, 0xbfb8aa3b, v166
	v_exp_f32_e32 v172, v172
	v_mul_f32_e32 v173, 0xbfb8aa3b, v167
	v_exp_f32_e32 v131, v131
	v_exp_f32_e32 v165, v165
	v_exp_f32_e32 v168, v168
	v_exp_f32_e32 v169, v169
	v_exp_f32_e32 v170, v170
	v_exp_f32_e32 v171, v171
	v_exp_f32_e32 v174, v173
	v_add_f32_e32 v172, 1.0, v172
	v_add_f32_e32 v131, 1.0, v131
	v_add_f32_e32 v165, 1.0, v165
	v_add_f32_e32 v168, 1.0, v168
	v_add_f32_e32 v169, 1.0, v169
	v_add_f32_e32 v170, 1.0, v170
	v_add_f32_e32 v171, 1.0, v171
	v_rcp_f32_e32 v173, v172
	v_add_f32_e32 v172, 1.0, v174
	v_rcp_f32_e32 v131, v131
	v_rcp_f32_e32 v165, v165
	v_rcp_f32_e32 v168, v168
	v_rcp_f32_e32 v169, v169
	v_rcp_f32_e32 v170, v170
	v_rcp_f32_e32 v171, v171
	v_rcp_f32_e32 v172, v172
	s_mov_b64 s[6:7], 0

; __device__ __forceinline__ float sigm_f(float v) { return __builtin_amdgcn_rcpf(1.0f + __builtin_amdgcn_exp2f(-1.44269504f * v)); }
; __device__ __forceinline__ float silu_f(float v) { return v * sigm_f(v); }
;     __device__ __forceinline__ void operator()(const f32x4 (&acc)[2][2][4][2], const Unit& u, int wr, int wc, int fr, int fq) const {
;     ...
; #pragma unroll
;                 for (int ai = 0; ai < 2; ++ai)
; #pragma unroll
;                     for (int m = 0; m < 4; ++m) { const int row = row0 + ai * HALF + m * 16; const float rsv = __builtin_amdgcn_rsqf(rs[row] * (1.0f / 1024.0f) + 1e-6f);
;                         bf16_t* rowp = O + (size_t)row * ldc + u.pn * BM + cw;
; #pragma unroll
;                         for (int bj = 0; bj < 2; ++bj) { f32x4 v0 = acc[ai][bj][m][0] * rsv, v1 = acc[ai][bj][m][1] * rsv;
;                             if (sub == 1) {
; #pragma unroll
;                                 for (int e = 0; e < 4; ++e) { v0[e] = silu_f(v0[e]); v1[e] = silu_f(v1[e]); } }
;                             else if (sub == 3) {
; #pragma unroll
;                                 for (int e = 0; e < 4; ++e) { v0[e] = sigm_f(v0[e]); v1[e] = sigm_f(v1[e]); } }
;                             store8(rowp + bj * HALF, v0, v1); } }
.LBB0_548:
	v_cvt_pk_bf16_f32 v136, v131, v168
	v_cvt_pk_bf16_f32 v137, v170, v173
	v_cvt_pk_bf16_f32 v138, v165, v169
	v_cvt_pk_bf16_f32 v139, v171, v172
	global_store_dwordx4 v[134:135], v[136:139], off offset:256
	s_cmp_gt_i32 s38, 2
	s_mov_b64 s[6:7], -1
	v_fmamk_f32 v131, v252, 0x3a800000, v237
	v_rsq_f32_e32 v132, v131
	s_nop 0
	v_pk_mul_f32 v[136:137], v[54:55], v[132:133] op_sel_hi:[1,0]
	v_pk_mul_f32 v[166:167], v[52:53], v[132:133] op_sel_hi:[1,0]
	v_pk_mul_f32 v[134:135], v[50:51], v[132:133] op_sel_hi:[1,0]
	v_pk_mul_f32 v[138:139], v[48:49], v[132:133] op_sel_hi:[1,0]
	s_cbranch_scc0 .LBB0_550
	v_mul_f32_e32 v133, 0xbfb8aa3b, v138
	v_exp_f32_e32 v133, v133
	v_mul_f32_e32 v165, 0xbfb8aa3b, v167
	v_exp_f32_e32 v168, v165
	v_mul_f32_e32 v165, 0xbfb8aa3b, v139
	v_exp_f32_e32 v169, v165
	v_add_f32_e32 v133, 1.0, v133
	v_rcp_f32_e32 v165, v133
	v_add_f32_e32 v133, 1.0, v168
	v_rcp_f32_e32 v168, v133
	v_add_f32_e32 v133, 1.0, v169
	v_mul_f32_e32 v169, 0xbfb8aa3b, v136
	v_exp_f32_e32 v170, v169
	v_mul_f32_e32 v169, 0xbfb8aa3b, v134
	v_exp_f32_e32 v171, v169
	v_rcp_f32_e32 v169, v133
	v_add_f32_e32 v133, 1.0, v170
	v_rcp_f32_e32 v170, v133
	v_add_f32_e32 v133, 1.0, v171
	v_mul_f32_e32 v171, 0xbfb8aa3b, v137
	v_mul_f32_e32 v131, 0xbfb8aa3b, v166
	v_exp_f32_e32 v172, v171
	v_mul_f32_e32 v171, 0xbfb8aa3b, v135
	v_exp_f32_e32 v131, v131
	v_exp_f32_e32 v174, v171
	v_rcp_f32_e32 v171, v133
	v_add_f32_e32 v133, 1.0, v172
	v_add_f32_e32 v131, 1.0, v131
	v_rcp_f32_e32 v173, v133
	v_add_f32_e32 v133, 1.0, v174
	v_rcp_f32_e32 v131, v131
	v_rcp_f32_e32 v172, v133
	s_mov_b64 s[6:7], 0

; __device__ __forceinline__ float sigm_f(float v) { return __builtin_amdgcn_rcpf(1.0f + __builtin_amdgcn_exp2f(-1.44269504f * v)); }
; __device__ __forceinline__ float silu_f(float v) { return v * sigm_f(v); }
;     __device__ __forceinline__ void operator()(const f32x4 (&acc)[2][2][4][2], const Unit& u, int wr, int wc, int fr, int fq) const {
;     ...
; #pragma unroll
;                 for (int ai = 0; ai < 2; ++ai)
; #pragma unroll
;                     for (int m = 0; m < 4; ++m) { const int row = row0 + ai * HALF + m * 16; const float rsv = __builtin_amdgcn_rsqf(rs[row] * (1.0f / 1024.0f) + 1e-6f);
;                         bf16_t* rowp = O + (size_t)row * ldc + u.pn * BM + cw;
; #pragma unroll
;                         for (int bj = 0; bj < 2; ++bj) { f32x4 v0 = acc[ai][bj][m][0] * rsv, v1 = acc[ai][bj][m][1] * rsv;
;                             if (sub == 1) {
; #pragma unroll
;                                 for (int e = 0; e < 4; ++e) { v0[e] = silu_f(v0[e]); v1[e] = silu_f(v1[e]); } }
;                             else if (sub == 3) {
; #pragma unroll
;                                 for (int e = 0; e < 4; ++e) { v0[e] = sigm_f(v0[e]); v1[e] = sigm_f(v1[e]); } }
;                             store8(rowp + bj * HALF, v0, v1); } }
.LBB0_554:
	v_add_u32_e32 v134, 0x90, v164
	v_mad_i64_i32 v[134:135], s[6:7], s82, v134, 0
	v_lshl_add_u64 v[134:135], v[134:135], 1, s[84:85]
	v_lshl_add_u64 v[134:135], s[62:63], 1, v[134:135]
	v_lshl_add_u64 v[134:135], v[148:149], 1, v[134:135]
	v_cvt_pk_bf16_f32 v136, v131, v168
	v_cvt_pk_bf16_f32 v137, v170, v173
	v_cvt_pk_bf16_f32 v138, v165, v169
	v_cvt_pk_bf16_f32 v139, v171, v172
	v_mov_b32_e32 v133, v132
	v_mov_b32_e32 v166, v132
	v_mov_b32_e32 v167, v132
	global_store_dwordx4 v[134:135], v[136:139], off
	s_cmp_gt_i32 s38, 2
	s_mov_b64 s[6:7], -1
	v_pk_mul_f32 v[136:137], v[30:31], v[166:167]
	v_pk_mul_f32 v[138:139], v[28:29], v[132:133]
	v_pk_mul_f32 v[166:167], v[26:27], v[166:167]
	v_pk_mul_f32 v[132:133], v[24:25], v[132:133]
	s_cbranch_scc0 .LBB0_556
	v_mul_f32_e32 v172, 0xbfb8aa3b, v137
	v_mul_f32_e32 v131, 0xbfb8aa3b, v138
	v_mul_f32_e32 v165, 0xbfb8aa3b, v132
	v_mul_f32_e32 v168, 0xbfb8aa3b, v139
	v_mul_f32_e32 v169, 0xbfb8aa3b, v133
	v_mul_f32_e32 v170, 0xbfb8aa3b, v136
	v_mul_f32_e32 v171, 0xbfb8aa3b, v166
	v_exp_f32_e32 v172, v172
	v_mul_f32_e32 v173, 0xbfb8aa3b, v167
	v_exp_f32_e32 v131, v131
	v_exp_f32_e32 v165, v165
	v_exp_f32_e32 v168, v168
	v_exp_f32_e32 v169, v169
	v_exp_f32_e32 v170, v170
	v_exp_f32_e32 v171, v171
	v_exp_f32_e32 v174, v173
	v_add_f32_e32 v172, 1.0, v172
	v_add_f32_e32 v131, 1.0, v131
	v_add_f32_e32 v165, 1.0, v165
	v_add_f32_e32 v168, 1.0, v168
	v_add_f32_e32 v169, 1.0, v169
	v_add_f32_e32 v170, 1.0, v170
	v_add_f32_e32 v171, 1.0, v171
	v_rcp_f32_e32 v173, v172
	v_add_f32_e32 v172, 1.0, v174
	v_rcp_f32_e32 v131, v131
	v_rcp_f32_e32 v165, v165
	v_rcp_f32_e32 v168, v168
	v_rcp_f32_e32 v169, v169
	v_rcp_f32_e32 v170, v170
	v_rcp_f32_e32 v171, v171
	v_rcp_f32_e32 v172, v172
	s_mov_b64 s[6:7], 0

; __device__ __forceinline__ float sigm_f(float v) { return __builtin_amdgcn_rcpf(1.0f + __builtin_amdgcn_exp2f(-1.44269504f * v)); }
; __device__ __forceinline__ float silu_f(float v) { return v * sigm_f(v); }
;     __device__ __forceinline__ void operator()(const f32x4 (&acc)[2][2][4][2], const Unit& u, int wr, int wc, int fr, int fq) const {
;     ...
; #pragma unroll
;                 for (int ai = 0; ai < 2; ++ai)
; #pragma unroll
;                     for (int m = 0; m < 4; ++m) { const int row = row0 + ai * HALF + m * 16; const float rsv = __builtin_amdgcn_rsqf(rs[row] * (1.0f / 1024.0f) + 1e-6f);
;                         bf16_t* rowp = O + (size_t)row * ldc + u.pn * BM + cw;
; #pragma unroll
;                         for (int bj = 0; bj < 2; ++bj) { f32x4 v0 = acc[ai][bj][m][0] * rsv, v1 = acc[ai][bj][m][1] * rsv;
;                             if (sub == 1) {
; #pragma unroll
;                                 for (int e = 0; e < 4; ++e) { v0[e] = silu_f(v0[e]); v1[e] = silu_f(v1[e]); } }
;                             else if (sub == 3) {
; #pragma unroll
;                                 for (int e = 0; e < 4; ++e) { v0[e] = sigm_f(v0[e]); v1[e] = sigm_f(v1[e]); } }
;                             store8(rowp + bj * HALF, v0, v1); } }
.LBB0_560:
	v_cvt_pk_bf16_f32 v136, v131, v168
	v_cvt_pk_bf16_f32 v137, v170, v173
	v_cvt_pk_bf16_f32 v138, v165, v169
	v_cvt_pk_bf16_f32 v139, v171, v172
	global_store_dwordx4 v[134:135], v[136:139], off offset:256
	s_cmp_gt_i32 s38, 2
	s_mov_b64 s[6:7], -1
	v_fmamk_f32 v131, v253, 0x3a800000, v237
	v_rsq_f32_e32 v132, v131
	s_nop 0
	v_pk_mul_f32 v[136:137], v[38:39], v[132:133] op_sel_hi:[1,0]
	v_pk_mul_f32 v[166:167], v[36:37], v[132:133] op_sel_hi:[1,0]
	v_pk_mul_f32 v[134:135], v[34:35], v[132:133] op_sel_hi:[1,0]
	v_pk_mul_f32 v[138:139], v[32:33], v[132:133] op_sel_hi:[1,0]
	s_cbranch_scc0 .LBB0_562
	v_mul_f32_e32 v133, 0xbfb8aa3b, v138
	v_exp_f32_e32 v133, v133
	v_mul_f32_e32 v165, 0xbfb8aa3b, v167
	v_exp_f32_e32 v168, v165
	v_mul_f32_e32 v165, 0xbfb8aa3b, v139
	v_exp_f32_e32 v169, v165
	v_add_f32_e32 v133, 1.0, v133
	v_rcp_f32_e32 v165, v133
	v_add_f32_e32 v133, 1.0, v168
	v_rcp_f32_e32 v168, v133
	v_add_f32_e32 v133, 1.0, v169
	v_mul_f32_e32 v169, 0xbfb8aa3b, v136
	v_exp_f32_e32 v170, v169
	v_mul_f32_e32 v169, 0xbfb8aa3b, v134
	v_exp_f32_e32 v171, v169
	v_rcp_f32_e32 v169, v133
	v_add_f32_e32 v133, 1.0, v170
	v_rcp_f32_e32 v170, v133
	v_add_f32_e32 v133, 1.0, v171
	v_mul_f32_e32 v171, 0xbfb8aa3b, v137
	v_mul_f32_e32 v131, 0xbfb8aa3b, v166
	v_exp_f32_e32 v172, v171
	v_mul_f32_e32 v171, 0xbfb8aa3b, v135
	v_exp_f32_e32 v131, v131
	v_exp_f32_e32 v174, v171
	v_rcp_f32_e32 v171, v133
	v_add_f32_e32 v133, 1.0, v172
	v_add_f32_e32 v131, 1.0, v131
	v_rcp_f32_e32 v173, v133
	v_add_f32_e32 v133, 1.0, v174
	v_rcp_f32_e32 v131, v131
	v_rcp_f32_e32 v172, v133
	s_mov_b64 s[6:7], 0

; __device__ __forceinline__ float sigm_f(float v) { return __builtin_amdgcn_rcpf(1.0f + __builtin_amdgcn_exp2f(-1.44269504f * v)); }
; __device__ __forceinline__ float silu_f(float v) { return v * sigm_f(v); }
;     __device__ __forceinline__ void operator()(const f32x4 (&acc)[2][2][4][2], const Unit& u, int wr, int wc, int fr, int fq) const {
;     ...
; #pragma unroll
;                 for (int ai = 0; ai < 2; ++ai)
; #pragma unroll
;                     for (int m = 0; m < 4; ++m) { const int row = row0 + ai * HALF + m * 16; const float rsv = __builtin_amdgcn_rsqf(rs[row] * (1.0f / 1024.0f) + 1e-6f);
;                         bf16_t* rowp = O + (size_t)row * ldc + u.pn * BM + cw;
; #pragma unroll
;                         for (int bj = 0; bj < 2; ++bj) { f32x4 v0 = acc[ai][bj][m][0] * rsv, v1 = acc[ai][bj][m][1] * rsv;
;                             if (sub == 1) {
; #pragma unroll
;                                 for (int e = 0; e < 4; ++e) { v0[e] = silu_f(v0[e]); v1[e] = silu_f(v1[e]); } }
;                             else if (sub == 3) {
; #pragma unroll
;                                 for (int e = 0; e < 4; ++e) { v0[e] = sigm_f(v0[e]); v1[e] = sigm_f(v1[e]); } }
;                             store8(rowp + bj * HALF, v0, v1); } }
.LBB0_566:
	v_add_u32_e32 v134, 0xa0, v164
	v_mad_i64_i32 v[134:135], s[6:7], s82, v134, 0
	v_lshl_add_u64 v[134:135], v[134:135], 1, s[84:85]
	v_lshl_add_u64 v[134:135], s[62:63], 1, v[134:135]
	v_lshl_add_u64 v[134:135], v[148:149], 1, v[134:135]
	v_cvt_pk_bf16_f32 v136, v131, v168
	v_cvt_pk_bf16_f32 v137, v170, v173
	v_cvt_pk_bf16_f32 v138, v165, v169
	v_cvt_pk_bf16_f32 v139, v171, v172
	v_mov_b32_e32 v133, v132
	v_mov_b32_e32 v166, v132
	v_mov_b32_e32 v167, v132
	global_store_dwordx4 v[134:135], v[136:139], off
	s_cmp_gt_i32 s38, 2
	s_mov_b64 s[6:7], -1
	v_pk_mul_f32 v[136:137], v[14:15], v[166:167]
	v_pk_mul_f32 v[138:139], v[12:13], v[132:133]
	v_pk_mul_f32 v[166:167], v[10:11], v[166:167]
	v_pk_mul_f32 v[132:133], v[8:9], v[132:133]
	s_cbranch_scc0 .LBB0_568
	v_mul_f32_e32 v172, 0xbfb8aa3b, v137
	v_mul_f32_e32 v131, 0xbfb8aa3b, v138
	v_mul_f32_e32 v165, 0xbfb8aa3b, v132
	v_mul_f32_e32 v168, 0xbfb8aa3b, v139
	v_mul_f32_e32 v169, 0xbfb8aa3b, v133
	v_mul_f32_e32 v170, 0xbfb8aa3b, v136
	v_mul_f32_e32 v171, 0xbfb8aa3b, v166
	v_exp_f32_e32 v172, v172
	v_mul_f32_e32 v173, 0xbfb8aa3b, v167
	v_exp_f32_e32 v131, v131
	v_exp_f32_e32 v165, v165
	v_exp_f32_e32 v168, v168
	v_exp_f32_e32 v169, v169
	v_exp_f32_e32 v170, v170
	v_exp_f32_e32 v171, v171
	v_exp_f32_e32 v174, v173
	v_add_f32_e32 v172, 1.0, v172
	v_add_f32_e32 v131, 1.0, v131
	v_add_f32_e32 v165, 1.0, v165
	v_add_f32_e32 v168, 1.0, v168
	v_add_f32_e32 v169, 1.0, v169
	v_add_f32_e32 v170, 1.0, v170
	v_add_f32_e32 v171, 1.0, v171
	v_rcp_f32_e32 v173, v172
	v_add_f32_e32 v172, 1.0, v174
	v_rcp_f32_e32 v131, v131
	v_rcp_f32_e32 v165, v165
	v_rcp_f32_e32 v168, v168
	v_rcp_f32_e32 v169, v169
	v_rcp_f32_e32 v170, v170
	v_rcp_f32_e32 v171, v171
	v_rcp_f32_e32 v172, v172
	s_mov_b64 s[6:7], 0

; __device__ __forceinline__ float sigm_f(float v) { return __builtin_amdgcn_rcpf(1.0f + __builtin_amdgcn_exp2f(-1.44269504f * v)); }
; __device__ __forceinline__ float silu_f(float v) { return v * sigm_f(v); }
;     __device__ __forceinline__ void operator()(const f32x4 (&acc)[2][2][4][2], const Unit& u, int wr, int wc, int fr, int fq) const {
;     ...
; #pragma unroll
;                 for (int ai = 0; ai < 2; ++ai)
; #pragma unroll
;                     for (int m = 0; m < 4; ++m) { const int row = row0 + ai * HALF + m * 16; const float rsv = __builtin_amdgcn_rsqf(rs[row] * (1.0f / 1024.0f) + 1e-6f);
;                         bf16_t* rowp = O + (size_t)row * ldc + u.pn * BM + cw;
; #pragma unroll
;                         for (int bj = 0; bj < 2; ++bj) { f32x4 v0 = acc[ai][bj][m][0] * rsv, v1 = acc[ai][bj][m][1] * rsv;
;                             if (sub == 1) {
; #pragma unroll
;                                 for (int e = 0; e < 4; ++e) { v0[e] = silu_f(v0[e]); v1[e] = silu_f(v1[e]); } }
;                             else if (sub == 3) {
; #pragma unroll
;                                 for (int e = 0; e < 4; ++e) { v0[e] = sigm_f(v0[e]); v1[e] = sigm_f(v1[e]); } }
;                             store8(rowp + bj * HALF, v0, v1); } }
.LBB0_572:
	v_cvt_pk_bf16_f32 v136, v131, v168
	v_cvt_pk_bf16_f32 v137, v170, v173
	v_cvt_pk_bf16_f32 v138, v165, v169
	v_cvt_pk_bf16_f32 v139, v171, v172
	global_store_dwordx4 v[134:135], v[136:139], off offset:256
	s_cmp_gt_i32 s38, 2
	s_mov_b64 s[6:7], -1
	v_fmamk_f32 v131, v255, 0x3a800000, v237
	v_rsq_f32_e32 v132, v131
	s_nop 0
	v_pk_mul_f32 v[136:137], v[22:23], v[132:133] op_sel_hi:[1,0]
	v_pk_mul_f32 v[166:167], v[20:21], v[132:133] op_sel_hi:[1,0]
	v_pk_mul_f32 v[134:135], v[18:19], v[132:133] op_sel_hi:[1,0]
	v_pk_mul_f32 v[138:139], v[16:17], v[132:133] op_sel_hi:[1,0]
	s_cbranch_scc0 .LBB0_574
	v_mul_f32_e32 v133, 0xbfb8aa3b, v138
	v_exp_f32_e32 v133, v133
	v_mul_f32_e32 v165, 0xbfb8aa3b, v167
	v_exp_f32_e32 v168, v165
	v_mul_f32_e32 v165, 0xbfb8aa3b, v139
	v_exp_f32_e32 v169, v165
	v_add_f32_e32 v133, 1.0, v133
	v_rcp_f32_e32 v165, v133
	v_add_f32_e32 v133, 1.0, v168
	v_rcp_f32_e32 v168, v133
	v_add_f32_e32 v133, 1.0, v169
	v_mul_f32_e32 v169, 0xbfb8aa3b, v136
	v_exp_f32_e32 v170, v169
	v_mul_f32_e32 v169, 0xbfb8aa3b, v134
	v_exp_f32_e32 v171, v169
	v_rcp_f32_e32 v169, v133
	v_add_f32_e32 v133, 1.0, v170
	v_rcp_f32_e32 v170, v133
	v_add_f32_e32 v133, 1.0, v171
	v_mul_f32_e32 v171, 0xbfb8aa3b, v137
	v_mul_f32_e32 v131, 0xbfb8aa3b, v166
	v_exp_f32_e32 v172, v171
	v_mul_f32_e32 v171, 0xbfb8aa3b, v135
	v_exp_f32_e32 v131, v131
	v_exp_f32_e32 v174, v171
	v_rcp_f32_e32 v171, v133
	v_add_f32_e32 v133, 1.0, v172
	v_add_f32_e32 v131, 1.0, v131
	v_rcp_f32_e32 v173, v133
	v_add_f32_e32 v133, 1.0, v174
	v_rcp_f32_e32 v131, v131
	v_rcp_f32_e32 v172, v133
	s_mov_b64 s[6:7], 0

; __device__ __forceinline__ float sigm_f(float v) { return __builtin_amdgcn_rcpf(1.0f + __builtin_amdgcn_exp2f(-1.44269504f * v)); }
; __device__ __forceinline__ float silu_f(float v) { return v * sigm_f(v); }
;     __device__ __forceinline__ void operator()(const f32x4 (&acc)[2][2][4][2], const Unit& u, int wr, int wc, int fr, int fq) const {
;     ...
; #pragma unroll
;                 for (int ai = 0; ai < 2; ++ai)
; #pragma unroll
;                     for (int m = 0; m < 4; ++m) { const int row = row0 + ai * HALF + m * 16; const float rsv = __builtin_amdgcn_rsqf(rs[row] * (1.0f / 1024.0f) + 1e-6f);
;                         bf16_t* rowp = O + (size_t)row * ldc + u.pn * BM + cw;
; #pragma unroll
;                         for (int bj = 0; bj < 2; ++bj) { f32x4 v0 = acc[ai][bj][m][0] * rsv, v1 = acc[ai][bj][m][1] * rsv;
;                             if (sub == 1) {
; #pragma unroll
;                                 for (int e = 0; e < 4; ++e) { v0[e] = silu_f(v0[e]); v1[e] = silu_f(v1[e]); } }
;                             else if (sub == 3) {
; #pragma unroll
;                                 for (int e = 0; e < 4; ++e) { v0[e] = sigm_f(v0[e]); v1[e] = sigm_f(v1[e]); } }
;                             store8(rowp + bj * HALF, v0, v1); } }
.LBB0_578:
	v_add_u32_e32 v134, 0xb0, v164
	v_mad_i64_i32 v[134:135], s[6:7], s82, v134, 0
	v_lshl_add_u64 v[134:135], v[134:135], 1, s[84:85]
	v_lshl_add_u64 v[134:135], s[62:63], 1, v[134:135]
	v_lshl_add_u64 v[134:135], v[148:149], 1, v[134:135]
	v_cvt_pk_bf16_f32 v136, v131, v168
	v_cvt_pk_bf16_f32 v137, v170, v173
	v_cvt_pk_bf16_f32 v138, v165, v169
	v_cvt_pk_bf16_f32 v139, v171, v172
	v_mov_b32_e32 v133, v132
	v_mov_b32_e32 v166, v132
	v_mov_b32_e32 v167, v132
	global_store_dwordx4 v[134:135], v[136:139], off
	s_cmp_gt_i32 s38, 2
	s_mov_b64 s[6:7], -1
	v_pk_mul_f32 v[136:137], v[6:7], v[166:167]
	v_pk_mul_f32 v[138:139], v[4:5], v[132:133]
	v_pk_mul_f32 v[166:167], v[2:3], v[166:167]
	v_pk_mul_f32 v[132:133], v[0:1], v[132:133]
	s_cbranch_scc0 .LBB0_580
	v_mul_f32_e32 v172, 0xbfb8aa3b, v137
	v_mul_f32_e32 v131, 0xbfb8aa3b, v138
	v_mul_f32_e32 v165, 0xbfb8aa3b, v132
	v_mul_f32_e32 v168, 0xbfb8aa3b, v139
	v_mul_f32_e32 v169, 0xbfb8aa3b, v133
	v_mul_f32_e32 v170, 0xbfb8aa3b, v136
	v_mul_f32_e32 v171, 0xbfb8aa3b, v166
	v_exp_f32_e32 v172, v172
	v_mul_f32_e32 v173, 0xbfb8aa3b, v167
	v_exp_f32_e32 v131, v131
	v_exp_f32_e32 v165, v165
	v_exp_f32_e32 v168, v168
	v_exp_f32_e32 v169, v169
	v_exp_f32_e32 v170, v170
	v_exp_f32_e32 v171, v171
	v_exp_f32_e32 v174, v173
	v_add_f32_e32 v172, 1.0, v172
	v_add_f32_e32 v131, 1.0, v131
	v_add_f32_e32 v165, 1.0, v165
	v_add_f32_e32 v168, 1.0, v168
	v_add_f32_e32 v169, 1.0, v169
	v_add_f32_e32 v170, 1.0, v170
	v_add_f32_e32 v171, 1.0, v171
	v_rcp_f32_e32 v173, v172
	v_add_f32_e32 v172, 1.0, v174
	v_rcp_f32_e32 v131, v131
	v_rcp_f32_e32 v165, v165
	v_rcp_f32_e32 v168, v168
	v_rcp_f32_e32 v169, v169
	v_rcp_f32_e32 v170, v170
	v_rcp_f32_e32 v171, v171
	v_rcp_f32_e32 v172, v172
	s_mov_b64 s[6:7], 0

;     __device__ __forceinline__ void operator()(const f32x4 (&acc)[2][2][4][2], const Unit& u, int wr, int wc, int fr, int fq) const {
;     ...
;             if (sub == 0) {
;                 const int i0 = 32 * (wc & 1) + 8 * fq;
; #pragma unroll
;                 for (int ai = 0; ai < 2; ++ai)
; #pragma unroll
;                     for (int m = 0; m < 4; ++m) { const int row = row0 + ai * HALF + m * 16; const float rsv = __builtin_amdgcn_rsqf(rs[row] * (1.0f / 1024.0f) + 1e-6f); const int pos = row & 2047;
;                         const f32x4 c0 = *(const f32x4*)(cs + pos * 64 + i0), c1 = *(const f32x4*)(cs + pos * 64 + i0 + 4);
;                         const f32x4 s0 = *(const f32x4*)(sn + pos * 64 + i0), s1 = *(const f32x4*)(sn + pos * 64 + i0 + 4);
;                         const f32x4 x1a = acc[ai][0][m][0] * rsv, x1b = acc[ai][0][m][1] * rsv, x2a = acc[ai][1][m][0] * rsv, x2b = acc[ai][1][m][1] * rsv;
;                         bf16_t* rowp = O + (size_t)row * ldc + u.pn * BM + cw;
;                         store8(rowp, x1a * c0 - x2a * s0, x1b * c1 - x2b * s1);
;                         store8(rowp + HALF, x1a * s0 + x2a * c0, x1b * s1 + x2b * c1); }
;     ...
;                             store8(rowp + bj * HALF, v0, v1); } }
.LBB0_584:
	v_cvt_pk_bf16_f32 v136, v131, v168
	v_cvt_pk_bf16_f32 v137, v170, v173
	v_cvt_pk_bf16_f32 v138, v165, v169
	v_cvt_pk_bf16_f32 v139, v171, v172
	global_store_dwordx4 v[134:135], v[136:139], off offset:256
	s_mov_b64 s[6:7], 0
.LBB0_585:
	s_and_b64 vcc, exec, s[6:7]
	s_cbranch_vccz .LBB0_587
	v_lshlrev_b32_e32 v131, 8, v164
	v_and_b32_e32 v176, 0x7cf00, v131
	v_lshl_add_u64 v[136:137], v[158:159], 0, v[176:177]
	flat_load_dwordx4 v[132:135], v[136:137]
	s_nop 0
	flat_load_dwordx4 v[136:139], v[136:137] offset:16
	v_lshl_add_u64 v[170:171], v[156:157], 0, v[176:177]
	flat_load_dwordx4 v[166:169], v[170:171]
	s_nop 0
	flat_load_dwordx4 v[170:173], v[170:171] offset:16
	s_ashr_i32 s7, s62, 31
	s_mov_b32 s6, s62
	v_pk_mul_f32 v[186:187], v[110:111], v[130:131] op_sel_hi:[1,0]
	v_pk_mul_f32 v[188:189], v[108:109], v[130:131] op_sel_hi:[1,0]
	v_pk_mul_f32 v[190:191], v[106:107], v[130:131] op_sel_hi:[1,0]
	v_pk_mul_f32 v[192:193], v[104:105], v[130:131] op_sel_hi:[1,0]
	v_mad_i64_i32 v[194:195], s[38:39], s82, v164, 0
	v_pk_mul_f32 v[174:175], v[126:127], v[130:131] op_sel_hi:[1,0]
	v_pk_mul_f32 v[178:179], v[124:125], v[130:131] op_sel_hi:[1,0]
	v_pk_mul_f32 v[182:183], v[122:123], v[130:131] op_sel_hi:[1,0]
	v_pk_mul_f32 v[184:185], v[120:121], v[130:131] op_sel_hi:[1,0]
	v_lshl_add_u64 v[194:195], v[194:195], 1, s[84:85]
	s_lshl_b64 s[6:7], s[6:7], 1
	v_lshlrev_b64 v[130:131], 1, v[148:149]
	v_lshl_add_u64 v[194:195], v[194:195], 0, s[6:7]
	v_lshl_add_u64 v[194:195], v[194:195], 0, v[130:131]
	s_waitcnt vmcnt(0) lgkmcnt(0)
	v_pk_mul_f32 v[196:197], v[186:187], v[134:135]
	v_pk_mul_f32 v[198:199], v[188:189], v[132:133]
	v_pk_mul_f32 v[200:201], v[190:191], v[138:139]
	v_pk_mul_f32 v[202:203], v[192:193], v[136:137]
	v_pk_mul_f32 v[134:135], v[174:175], v[134:135]
	v_pk_mul_f32 v[132:133], v[178:179], v[132:133]
	v_pk_mul_f32 v[138:139], v[182:183], v[138:139]
	v_pk_mul_f32 v[136:137], v[184:185], v[136:137]
	v_pk_fma_f32 v[174:175], v[174:175], v[168:169], v[196:197] neg_lo:[0,0,1] neg_hi:[0,0,1]
	v_pk_fma_f32 v[178:179], v[178:179], v[166:167], v[198:199] neg_lo:[0,0,1] neg_hi:[0,0,1]
	v_pk_fma_f32 v[182:183], v[182:183], v[172:173], v[200:201] neg_lo:[0,0,1] neg_hi:[0,0,1]
	v_pk_fma_f32 v[184:185], v[184:185], v[170:171], v[202:203] neg_lo:[0,0,1] neg_hi:[0,0,1]
	v_pk_fma_f32 v[168:169], v[186:187], v[168:169], v[134:135]
	v_pk_fma_f32 v[166:167], v[188:189], v[166:167], v[132:133]
	v_pk_fma_f32 v[172:173], v[190:191], v[172:173], v[138:139]
	v_pk_fma_f32 v[138:139], v[192:193], v[170:171], v[136:137]
	v_cvt_pk_bf16_f32 v132, v178, v179
	v_cvt_pk_bf16_f32 v133, v174, v175
	v_cvt_pk_bf16_f32 v134, v184, v185
	v_cvt_pk_bf16_f32 v135, v182, v183
	v_cvt_pk_bf16_f32 v136, v166, v167
	v_cvt_pk_bf16_f32 v137, v168, v169
	v_cvt_pk_bf16_f32 v138, v138, v139
	v_cvt_pk_bf16_f32 v139, v172, v173
	global_store_dwordx4 v[194:195], v[132:135], off
	global_store_dwordx4 v[194:195], v[136:139], off offset:256
	flat_load_dword v165, v[128:129] offset:64
	v_or_b32_e32 v174, 16, v164
	v_lshlrev_b32_e32 v132, 8, v174
	v_and_b32_e32 v176, 0x7df00, v132
	v_lshl_add_u64 v[136:137], v[158:159], 0, v[176:177]
	flat_load_dwordx4 v[132:135], v[136:137]
	s_nop 0
	flat_load_dwordx4 v[136:139], v[136:137] offset:16
	v_lshl_add_u64 v[170:171], v[156:157], 0, v[176:177]
	flat_load_dwordx4 v[166:169], v[170:171]
	s_nop 0
	flat_load_dwordx4 v[170:173], v[170:171] offset:16
	v_mad_i64_i32 v[174:175], s[38:39], s82, v174, 0
	v_lshl_add_u64 v[174:175], v[174:175], 1, s[84:85]
	v_lshl_add_u64 v[174:175], v[174:175], 0, s[6:7]
	v_lshl_add_u64 v[174:175], v[174:175], 0, v[130:131]
	s_waitcnt vmcnt(0) lgkmcnt(0)
	v_fmamk_f32 v165, v165, 0x3a800000, v237
	v_rsq_f32_e32 v176, v165
	s_nop 0
	v_pk_mul_f32 v[188:189], v[92:93], v[176:177] op_sel_hi:[1,0]
	v_pk_mul_f32 v[190:191], v[94:95], v[176:177] op_sel_hi:[1,0]
	v_pk_mul_f32 v[192:193], v[88:89], v[176:177] op_sel_hi:[1,0]
	v_pk_mul_f32 v[194:195], v[90:91], v[176:177] op_sel_hi:[1,0]
	v_pk_mul_f32 v[178:179], v[116:117], v[176:177] op_sel_hi:[1,0]
	v_pk_mul_f32 v[182:183], v[118:119], v[176:177] op_sel_hi:[1,0]
	v_pk_mul_f32 v[184:185], v[112:113], v[176:177] op_sel_hi:[1,0]
	v_pk_mul_f32 v[186:187], v[114:115], v[176:177] op_sel_hi:[1,0]
	v_pk_mul_f32 v[196:197], v[134:135], v[190:191]
	v_pk_mul_f32 v[198:199], v[132:133], v[188:189]
	v_pk_mul_f32 v[200:201], v[138:139], v[194:195]
	v_pk_mul_f32 v[202:203], v[136:137], v[192:193]
	v_pk_mul_f32 v[190:191], v[168:169], v[190:191]
	v_pk_mul_f32 v[188:189], v[166:167], v[188:189]
	v_pk_mul_f32 v[194:195], v[172:173], v[194:195]
	v_pk_mul_f32 v[192:193], v[170:171], v[192:193]
	v_pk_fma_f32 v[168:169], v[168:169], v[182:183], v[196:197] neg_lo:[0,0,1] neg_hi:[0,0,1]
	v_pk_fma_f32 v[166:167], v[166:167], v[178:179], v[198:199] neg_lo:[0,0,1] neg_hi:[0,0,1]
	v_pk_fma_f32 v[172:173], v[172:173], v[186:187], v[200:201] neg_lo:[0,0,1] neg_hi:[0,0,1]
	v_pk_fma_f32 v[170:171], v[170:171], v[184:185], v[202:203] neg_lo:[0,0,1] neg_hi:[0,0,1]
	v_pk_fma_f32 v[182:183], v[134:135], v[182:183], v[190:191]
	v_pk_fma_f32 v[178:179], v[132:133], v[178:179], v[188:189]
	v_pk_fma_f32 v[186:187], v[138:139], v[186:187], v[194:195]
	v_pk_fma_f32 v[138:139], v[136:137], v[184:185], v[192:193]
	v_cvt_pk_bf16_f32 v132, v166, v167
	v_cvt_pk_bf16_f32 v133, v168, v169
	v_cvt_pk_bf16_f32 v134, v170, v171
	v_cvt_pk_bf16_f32 v135, v172, v173
	v_cvt_pk_bf16_f32 v136, v178, v179
	v_cvt_pk_bf16_f32 v137, v182, v183
	v_cvt_pk_bf16_f32 v138, v138, v139
	v_cvt_pk_bf16_f32 v139, v186, v187
	global_store_dwordx4 v[174:175], v[132:135], off
	global_store_dwordx4 v[174:175], v[136:139], off offset:256
	flat_load_dword v165, v[128:129] offset:128
	v_or_b32_e32 v174, 32, v164
	v_lshlrev_b32_e32 v132, 8, v174
	v_and_b32_e32 v176, 0x7ef00, v132
	v_lshl_add_u64 v[136:137], v[158:159], 0, v[176:177]
	flat_load_dwordx4 v[132:135], v[136:137]
	s_nop 0
	flat_load_dwordx4 v[136:139], v[136:137] offset:16
	v_lshl_add_u64 v[170:171], v[156:157], 0, v[176:177]
	flat_load_dwordx4 v[166:169], v[170:171]
	s_nop 0
	flat_load_dwordx4 v[170:173], v[170:171] offset:16
	v_mad_i64_i32 v[174:175], s[38:39], s82, v174, 0
	v_lshl_add_u64 v[174:175], v[174:175], 1, s[84:85]
	v_lshl_add_u64 v[174:175], v[174:175], 0, s[6:7]
	v_lshl_add_u64 v[174:175], v[174:175], 0, v[130:131]
	s_waitcnt vmcnt(0) lgkmcnt(0)
;     __device__ __forceinline__ void operator()(const f32x4 (&acc)[2][2][4][2], const Unit& u, int wr, int wc, int fr, int fq) const {
;     ...
; #pragma unroll
;                 for (int ai = 0; ai < 2; ++ai)
; #pragma unroll
;                     for (int m = 0; m < 4; ++m) { const int row = row0 + ai * HALF + m * 16; const float rsv = __builtin_amdgcn_rsqf(rs[row] * (1.0f / 1024.0f) + 1e-6f); const int pos = row & 2047;
;                         const f32x4 c0 = *(const f32x4*)(cs + pos * 64 + i0), c1 = *(const f32x4*)(cs + pos * 64 + i0 + 4);
;                         const f32x4 s0 = *(const f32x4*)(sn + pos * 64 + i0), s1 = *(const f32x4*)(sn + pos * 64 + i0 + 4);
;                         const f32x4 x1a = acc[ai][0][m][0] * rsv, x1b = acc[ai][0][m][1] * rsv, x2a = acc[ai][1][m][0] * rsv, x2b = acc[ai][1][m][1] * rsv;
;                         bf16_t* rowp = O + (size_t)row * ldc + u.pn * BM + cw;
;                         store8(rowp, x1a * c0 - x2a * s0, x1b * c1 - x2b * s1);
;                         store8(rowp + HALF, x1a * s0 + x2a * c0, x1b * s1 + x2b * c1); }
	v_fmamk_f32 v165, v165, 0x3a800000, v237
	v_rsq_f32_e32 v176, v165
	s_nop 0
	v_pk_mul_f32 v[188:189], v[76:77], v[176:177] op_sel_hi:[1,0]
	v_pk_mul_f32 v[190:191], v[78:79], v[176:177] op_sel_hi:[1,0]
	v_pk_mul_f32 v[192:193], v[72:73], v[176:177] op_sel_hi:[1,0]
	v_pk_mul_f32 v[194:195], v[74:75], v[176:177] op_sel_hi:[1,0]
	v_pk_mul_f32 v[178:179], v[100:101], v[176:177] op_sel_hi:[1,0]
	v_pk_mul_f32 v[182:183], v[102:103], v[176:177] op_sel_hi:[1,0]
	v_pk_mul_f32 v[184:185], v[96:97], v[176:177] op_sel_hi:[1,0]
	v_pk_mul_f32 v[186:187], v[98:99], v[176:177] op_sel_hi:[1,0]
	v_pk_mul_f32 v[196:197], v[134:135], v[190:191]
	v_pk_mul_f32 v[198:199], v[132:133], v[188:189]
	v_pk_mul_f32 v[200:201], v[138:139], v[194:195]
	v_pk_mul_f32 v[202:203], v[136:137], v[192:193]
	v_pk_mul_f32 v[190:191], v[168:169], v[190:191]
	v_pk_mul_f32 v[188:189], v[166:167], v[188:189]
	v_pk_mul_f32 v[194:195], v[172:173], v[194:195]
	v_pk_mul_f32 v[192:193], v[170:171], v[192:193]
	v_pk_fma_f32 v[168:169], v[168:169], v[182:183], v[196:197] neg_lo:[0,0,1] neg_hi:[0,0,1]
	v_pk_fma_f32 v[166:167], v[166:167], v[178:179], v[198:199] neg_lo:[0,0,1] neg_hi:[0,0,1]
	v_pk_fma_f32 v[172:173], v[172:173], v[186:187], v[200:201] neg_lo:[0,0,1] neg_hi:[0,0,1]
	v_pk_fma_f32 v[170:171], v[170:171], v[184:185], v[202:203] neg_lo:[0,0,1] neg_hi:[0,0,1]
	v_pk_fma_f32 v[182:183], v[134:135], v[182:183], v[190:191]
	v_pk_fma_f32 v[178:179], v[132:133], v[178:179], v[188:189]
	v_pk_fma_f32 v[186:187], v[138:139], v[186:187], v[194:195]
	v_pk_fma_f32 v[138:139], v[136:137], v[184:185], v[192:193]
	v_cvt_pk_bf16_f32 v132, v166, v167
	v_cvt_pk_bf16_f32 v133, v168, v169
	v_cvt_pk_bf16_f32 v134, v170, v171
	v_cvt_pk_bf16_f32 v135, v172, v173
	v_cvt_pk_bf16_f32 v136, v178, v179
	v_cvt_pk_bf16_f32 v137, v182, v183
	v_cvt_pk_bf16_f32 v138, v138, v139
	v_cvt_pk_bf16_f32 v139, v186, v187
	global_store_dwordx4 v[174:175], v[132:135], off
	global_store_dwordx4 v[174:175], v[136:139], off offset:256
	flat_load_dword v165, v[128:129] offset:192
	v_or_b32_e32 v174, 48, v164
	v_lshlrev_b32_e32 v132, 8, v174
	v_and_b32_e32 v176, 0x7ff00, v132
	v_lshl_add_u64 v[136:137], v[158:159], 0, v[176:177]
	flat_load_dwordx4 v[132:135], v[136:137]
	s_nop 0
	flat_load_dwordx4 v[136:139], v[136:137] offset:16
	v_lshl_add_u64 v[170:171], v[156:157], 0, v[176:177]
	flat_load_dwordx4 v[166:169], v[170:171]
	s_nop 0
	flat_load_dwordx4 v[170:173], v[170:171] offset:16
	v_mad_i64_i32 v[174:175], s[38:39], s82, v174, 0
	v_lshl_add_u64 v[174:175], v[174:175], 1, s[84:85]
	v_lshl_add_u64 v[174:175], v[174:175], 0, s[6:7]
	v_lshl_add_u64 v[174:175], v[174:175], 0, v[130:131]
	s_waitcnt vmcnt(0) lgkmcnt(0)
	v_fmamk_f32 v165, v165, 0x3a800000, v237
	v_rsq_f32_e32 v176, v165
	s_nop 0
	v_pk_mul_f32 v[188:189], v[68:69], v[176:177] op_sel_hi:[1,0]
	v_pk_mul_f32 v[190:191], v[70:71], v[176:177] op_sel_hi:[1,0]
	v_pk_mul_f32 v[192:193], v[64:65], v[176:177] op_sel_hi:[1,0]
	v_pk_mul_f32 v[194:195], v[66:67], v[176:177] op_sel_hi:[1,0]
	v_pk_mul_f32 v[178:179], v[84:85], v[176:177] op_sel_hi:[1,0]
	v_pk_mul_f32 v[182:183], v[86:87], v[176:177] op_sel_hi:[1,0]
	v_pk_mul_f32 v[184:185], v[80:81], v[176:177] op_sel_hi:[1,0]
	v_pk_mul_f32 v[186:187], v[82:83], v[176:177] op_sel_hi:[1,0]
	v_pk_mul_f32 v[196:197], v[134:135], v[190:191]
	v_pk_mul_f32 v[198:199], v[132:133], v[188:189]
	v_pk_mul_f32 v[200:201], v[138:139], v[194:195]
	v_pk_mul_f32 v[202:203], v[136:137], v[192:193]
	v_pk_mul_f32 v[190:191], v[168:169], v[190:191]
	v_pk_mul_f32 v[188:189], v[166:167], v[188:189]
	v_pk_mul_f32 v[194:195], v[172:173], v[194:195]
	v_pk_mul_f32 v[192:193], v[170:171], v[192:193]
	v_pk_fma_f32 v[168:169], v[168:169], v[182:183], v[196:197] neg_lo:[0,0,1] neg_hi:[0,0,1]
	v_pk_fma_f32 v[166:167], v[166:167], v[178:179], v[198:199] neg_lo:[0,0,1] neg_hi:[0,0,1]
	v_pk_fma_f32 v[172:173], v[172:173], v[186:187], v[200:201] neg_lo:[0,0,1] neg_hi:[0,0,1]
	v_pk_fma_f32 v[170:171], v[170:171], v[184:185], v[202:203] neg_lo:[0,0,1] neg_hi:[0,0,1]
	v_pk_fma_f32 v[182:183], v[134:135], v[182:183], v[190:191]
	v_pk_fma_f32 v[178:179], v[132:133], v[178:179], v[188:189]
	v_pk_fma_f32 v[186:187], v[138:139], v[186:187], v[194:195]
	v_pk_fma_f32 v[138:139], v[136:137], v[184:185], v[192:193]
	v_cvt_pk_bf16_f32 v132, v166, v167
	v_cvt_pk_bf16_f32 v133, v168, v169
	v_cvt_pk_bf16_f32 v134, v170, v171
	v_cvt_pk_bf16_f32 v135, v172, v173
	v_cvt_pk_bf16_f32 v136, v178, v179
	v_cvt_pk_bf16_f32 v137, v182, v183
	v_cvt_pk_bf16_f32 v138, v138, v139
	v_cvt_pk_bf16_f32 v139, v186, v187
	global_store_dwordx4 v[174:175], v[132:135], off
	global_store_dwordx4 v[174:175], v[136:139], off offset:256
	flat_load_dword v165, v[128:129] offset:512
	v_add_u32_e32 v174, 0x80, v164
	v_lshlrev_b32_e32 v132, 8, v174
	v_and_b32_e32 v176, 0x7cf00, v132
	v_lshl_add_u64 v[136:137], v[158:159], 0, v[176:177]
	flat_load_dwordx4 v[132:135], v[136:137]
	s_nop 0
	flat_load_dwordx4 v[136:139], v[136:137] offset:16
	v_lshl_add_u64 v[170:171], v[156:157], 0, v[176:177]
	flat_load_dwordx4 v[166:169], v[170:171]
	s_nop 0
	flat_load_dwordx4 v[170:173], v[170:171] offset:16
	v_mad_i64_i32 v[174:175], s[38:39], s82, v174, 0
	v_lshl_add_u64 v[174:175], v[174:175], 1, s[84:85]
	v_lshl_add_u64 v[174:175], v[174:175], 0, s[6:7]
	v_lshl_add_u64 v[174:175], v[174:175], 0, v[130:131]
	s_waitcnt vmcnt(0) lgkmcnt(0)
;     __device__ __forceinline__ void operator()(const f32x4 (&acc)[2][2][4][2], const Unit& u, int wr, int wc, int fr, int fq) const {
;     ...
; #pragma unroll
;                 for (int ai = 0; ai < 2; ++ai)
; #pragma unroll
;                     for (int m = 0; m < 4; ++m) { const int row = row0 + ai * HALF + m * 16; const float rsv = __builtin_amdgcn_rsqf(rs[row] * (1.0f / 1024.0f) + 1e-6f); const int pos = row & 2047;
;                         const f32x4 c0 = *(const f32x4*)(cs + pos * 64 + i0), c1 = *(const f32x4*)(cs + pos * 64 + i0 + 4);
;                         const f32x4 s0 = *(const f32x4*)(sn + pos * 64 + i0), s1 = *(const f32x4*)(sn + pos * 64 + i0 + 4);
;                         const f32x4 x1a = acc[ai][0][m][0] * rsv, x1b = acc[ai][0][m][1] * rsv, x2a = acc[ai][1][m][0] * rsv, x2b = acc[ai][1][m][1] * rsv;
;                         bf16_t* rowp = O + (size_t)row * ldc + u.pn * BM + cw;
;                         store8(rowp, x1a * c0 - x2a * s0, x1b * c1 - x2b * s1);
;                         store8(rowp + HALF, x1a * s0 + x2a * c0, x1b * s1 + x2b * c1); }
	v_fmamk_f32 v165, v165, 0x3a800000, v237
	v_rsq_f32_e32 v176, v165
	s_nop 0
	v_pk_mul_f32 v[188:189], v[44:45], v[176:177] op_sel_hi:[1,0]
	v_pk_mul_f32 v[190:191], v[46:47], v[176:177] op_sel_hi:[1,0]
	v_pk_mul_f32 v[192:193], v[40:41], v[176:177] op_sel_hi:[1,0]
	v_pk_mul_f32 v[194:195], v[42:43], v[176:177] op_sel_hi:[1,0]
	v_pk_mul_f32 v[178:179], v[60:61], v[176:177] op_sel_hi:[1,0]
	v_pk_mul_f32 v[182:183], v[62:63], v[176:177] op_sel_hi:[1,0]
	v_pk_mul_f32 v[184:185], v[56:57], v[176:177] op_sel_hi:[1,0]
	v_pk_mul_f32 v[186:187], v[58:59], v[176:177] op_sel_hi:[1,0]
	v_pk_mul_f32 v[196:197], v[134:135], v[190:191]
	v_pk_mul_f32 v[198:199], v[132:133], v[188:189]
	v_pk_mul_f32 v[200:201], v[138:139], v[194:195]
	v_pk_mul_f32 v[202:203], v[136:137], v[192:193]
	v_pk_mul_f32 v[190:191], v[168:169], v[190:191]
	v_pk_mul_f32 v[188:189], v[166:167], v[188:189]
	v_pk_mul_f32 v[194:195], v[172:173], v[194:195]
	v_pk_mul_f32 v[192:193], v[170:171], v[192:193]
	v_pk_fma_f32 v[168:169], v[168:169], v[182:183], v[196:197] neg_lo:[0,0,1] neg_hi:[0,0,1]
	v_pk_fma_f32 v[166:167], v[166:167], v[178:179], v[198:199] neg_lo:[0,0,1] neg_hi:[0,0,1]
	v_pk_fma_f32 v[172:173], v[172:173], v[186:187], v[200:201] neg_lo:[0,0,1] neg_hi:[0,0,1]
	v_pk_fma_f32 v[170:171], v[170:171], v[184:185], v[202:203] neg_lo:[0,0,1] neg_hi:[0,0,1]
	v_pk_fma_f32 v[182:183], v[134:135], v[182:183], v[190:191]
	v_pk_fma_f32 v[178:179], v[132:133], v[178:179], v[188:189]
	v_pk_fma_f32 v[186:187], v[138:139], v[186:187], v[194:195]
	v_pk_fma_f32 v[138:139], v[136:137], v[184:185], v[192:193]
	v_cvt_pk_bf16_f32 v132, v166, v167
	v_cvt_pk_bf16_f32 v133, v168, v169
	v_cvt_pk_bf16_f32 v134, v170, v171
	v_cvt_pk_bf16_f32 v135, v172, v173
	v_cvt_pk_bf16_f32 v136, v178, v179
	v_cvt_pk_bf16_f32 v137, v182, v183
	v_cvt_pk_bf16_f32 v138, v138, v139
	v_cvt_pk_bf16_f32 v139, v186, v187
	global_store_dwordx4 v[174:175], v[132:135], off
	global_store_dwordx4 v[174:175], v[136:139], off offset:256
	flat_load_dword v165, v[128:129] offset:576
	v_add_u32_e32 v174, 0x90, v164
	v_lshlrev_b32_e32 v132, 8, v174
	v_and_b32_e32 v176, 0x7df00, v132
	v_lshl_add_u64 v[136:137], v[158:159], 0, v[176:177]
	flat_load_dwordx4 v[132:135], v[136:137]
	s_nop 0
	flat_load_dwordx4 v[136:139], v[136:137] offset:16
	v_lshl_add_u64 v[170:171], v[156:157], 0, v[176:177]
	flat_load_dwordx4 v[166:169], v[170:171]
	s_nop 0
	flat_load_dwordx4 v[170:173], v[170:171] offset:16
	v_mad_i64_i32 v[174:175], s[38:39], s82, v174, 0
	v_lshl_add_u64 v[174:175], v[174:175], 1, s[84:85]
	v_lshl_add_u64 v[174:175], v[174:175], 0, s[6:7]
	v_lshl_add_u64 v[174:175], v[174:175], 0, v[130:131]
	s_waitcnt vmcnt(0) lgkmcnt(0)
	v_fmamk_f32 v165, v165, 0x3a800000, v237
	v_rsq_f32_e32 v176, v165
	s_nop 0
	v_pk_mul_f32 v[188:189], v[28:29], v[176:177] op_sel_hi:[1,0]
	v_pk_mul_f32 v[190:191], v[30:31], v[176:177] op_sel_hi:[1,0]
	v_pk_mul_f32 v[192:193], v[24:25], v[176:177] op_sel_hi:[1,0]
	v_pk_mul_f32 v[194:195], v[26:27], v[176:177] op_sel_hi:[1,0]
	v_pk_mul_f32 v[178:179], v[52:53], v[176:177] op_sel_hi:[1,0]
	v_pk_mul_f32 v[182:183], v[54:55], v[176:177] op_sel_hi:[1,0]
	v_pk_mul_f32 v[184:185], v[48:49], v[176:177] op_sel_hi:[1,0]
	v_pk_mul_f32 v[186:187], v[50:51], v[176:177] op_sel_hi:[1,0]
	v_pk_mul_f32 v[196:197], v[134:135], v[190:191]
	v_pk_mul_f32 v[198:199], v[132:133], v[188:189]
	v_pk_mul_f32 v[200:201], v[138:139], v[194:195]
	v_pk_mul_f32 v[202:203], v[136:137], v[192:193]
	v_pk_mul_f32 v[190:191], v[168:169], v[190:191]
	v_pk_mul_f32 v[188:189], v[166:167], v[188:189]
	v_pk_mul_f32 v[194:195], v[172:173], v[194:195]
	v_pk_mul_f32 v[192:193], v[170:171], v[192:193]
	v_pk_fma_f32 v[168:169], v[168:169], v[182:183], v[196:197] neg_lo:[0,0,1] neg_hi:[0,0,1]
	v_pk_fma_f32 v[166:167], v[166:167], v[178:179], v[198:199] neg_lo:[0,0,1] neg_hi:[0,0,1]
	v_pk_fma_f32 v[172:173], v[172:173], v[186:187], v[200:201] neg_lo:[0,0,1] neg_hi:[0,0,1]
	v_pk_fma_f32 v[170:171], v[170:171], v[184:185], v[202:203] neg_lo:[0,0,1] neg_hi:[0,0,1]
	v_pk_fma_f32 v[182:183], v[134:135], v[182:183], v[190:191]
	v_pk_fma_f32 v[178:179], v[132:133], v[178:179], v[188:189]
	v_pk_fma_f32 v[186:187], v[138:139], v[186:187], v[194:195]
	v_pk_fma_f32 v[138:139], v[136:137], v[184:185], v[192:193]
	v_cvt_pk_bf16_f32 v132, v166, v167
	v_cvt_pk_bf16_f32 v133, v168, v169
	v_cvt_pk_bf16_f32 v134, v170, v171
	v_cvt_pk_bf16_f32 v135, v172, v173
	v_cvt_pk_bf16_f32 v136, v178, v179
	v_cvt_pk_bf16_f32 v137, v182, v183
	v_cvt_pk_bf16_f32 v138, v138, v139
	v_cvt_pk_bf16_f32 v139, v186, v187
	global_store_dwordx4 v[174:175], v[132:135], off
	global_store_dwordx4 v[174:175], v[136:139], off offset:256
	flat_load_dword v165, v[128:129] offset:640
	v_add_u32_e32 v174, 0xa0, v164
	v_lshlrev_b32_e32 v132, 8, v174
	v_and_b32_e32 v176, 0x7ef00, v132
	v_lshl_add_u64 v[136:137], v[158:159], 0, v[176:177]
	flat_load_dwordx4 v[132:135], v[136:137]
	s_nop 0
	flat_load_dwordx4 v[136:139], v[136:137] offset:16
	v_lshl_add_u64 v[170:171], v[156:157], 0, v[176:177]
	flat_load_dwordx4 v[166:169], v[170:171]
	s_nop 0
	flat_load_dwordx4 v[170:173], v[170:171] offset:16
	v_mad_i64_i32 v[174:175], s[38:39], s82, v174, 0
	v_lshl_add_u64 v[174:175], v[174:175], 1, s[84:85]
	v_lshl_add_u64 v[174:175], v[174:175], 0, s[6:7]
	v_lshl_add_u64 v[174:175], v[174:175], 0, v[130:131]
	s_waitcnt vmcnt(0) lgkmcnt(0)
;     __device__ __forceinline__ void operator()(const f32x4 (&acc)[2][2][4][2], const Unit& u, int wr, int wc, int fr, int fq) const {
;     ...
; #pragma unroll
;                 for (int ai = 0; ai < 2; ++ai)
; #pragma unroll
;                     for (int m = 0; m < 4; ++m) { const int row = row0 + ai * HALF + m * 16; const float rsv = __builtin_amdgcn_rsqf(rs[row] * (1.0f / 1024.0f) + 1e-6f); const int pos = row & 2047;
;                         const f32x4 c0 = *(const f32x4*)(cs + pos * 64 + i0), c1 = *(const f32x4*)(cs + pos * 64 + i0 + 4);
;                         const f32x4 s0 = *(const f32x4*)(sn + pos * 64 + i0), s1 = *(const f32x4*)(sn + pos * 64 + i0 + 4);
;                         const f32x4 x1a = acc[ai][0][m][0] * rsv, x1b = acc[ai][0][m][1] * rsv, x2a = acc[ai][1][m][0] * rsv, x2b = acc[ai][1][m][1] * rsv;
;                         bf16_t* rowp = O + (size_t)row * ldc + u.pn * BM + cw;
;                         store8(rowp, x1a * c0 - x2a * s0, x1b * c1 - x2b * s1);
;                         store8(rowp + HALF, x1a * s0 + x2a * c0, x1b * s1 + x2b * c1); }
	v_fmamk_f32 v165, v165, 0x3a800000, v237
	v_rsq_f32_e32 v176, v165
	s_nop 0
	v_pk_mul_f32 v[188:189], v[12:13], v[176:177] op_sel_hi:[1,0]
	v_pk_mul_f32 v[190:191], v[14:15], v[176:177] op_sel_hi:[1,0]
	v_pk_mul_f32 v[192:193], v[8:9], v[176:177] op_sel_hi:[1,0]
	v_pk_mul_f32 v[194:195], v[10:11], v[176:177] op_sel_hi:[1,0]
	v_pk_mul_f32 v[178:179], v[36:37], v[176:177] op_sel_hi:[1,0]
	v_pk_mul_f32 v[182:183], v[38:39], v[176:177] op_sel_hi:[1,0]
	v_pk_mul_f32 v[184:185], v[32:33], v[176:177] op_sel_hi:[1,0]
	v_pk_mul_f32 v[186:187], v[34:35], v[176:177] op_sel_hi:[1,0]
	v_pk_mul_f32 v[196:197], v[134:135], v[190:191]
	v_pk_mul_f32 v[198:199], v[132:133], v[188:189]
	v_pk_mul_f32 v[200:201], v[138:139], v[194:195]
	v_pk_mul_f32 v[202:203], v[136:137], v[192:193]
	v_pk_mul_f32 v[190:191], v[168:169], v[190:191]
	v_pk_mul_f32 v[188:189], v[166:167], v[188:189]
	v_pk_mul_f32 v[194:195], v[172:173], v[194:195]
	v_pk_mul_f32 v[192:193], v[170:171], v[192:193]
	v_pk_fma_f32 v[168:169], v[168:169], v[182:183], v[196:197] neg_lo:[0,0,1] neg_hi:[0,0,1]
	v_pk_fma_f32 v[166:167], v[166:167], v[178:179], v[198:199] neg_lo:[0,0,1] neg_hi:[0,0,1]
	v_pk_fma_f32 v[172:173], v[172:173], v[186:187], v[200:201] neg_lo:[0,0,1] neg_hi:[0,0,1]
	v_pk_fma_f32 v[170:171], v[170:171], v[184:185], v[202:203] neg_lo:[0,0,1] neg_hi:[0,0,1]
	v_pk_fma_f32 v[182:183], v[134:135], v[182:183], v[190:191]
	v_pk_fma_f32 v[178:179], v[132:133], v[178:179], v[188:189]
	v_pk_fma_f32 v[186:187], v[138:139], v[186:187], v[194:195]
	v_pk_fma_f32 v[138:139], v[136:137], v[184:185], v[192:193]
	v_cvt_pk_bf16_f32 v132, v166, v167
	v_cvt_pk_bf16_f32 v133, v168, v169
	v_cvt_pk_bf16_f32 v134, v170, v171
	v_cvt_pk_bf16_f32 v135, v172, v173
	v_cvt_pk_bf16_f32 v136, v178, v179
	v_cvt_pk_bf16_f32 v137, v182, v183
	v_cvt_pk_bf16_f32 v138, v138, v139
	v_cvt_pk_bf16_f32 v139, v186, v187
	global_store_dwordx4 v[174:175], v[132:135], off
	global_store_dwordx4 v[174:175], v[136:139], off offset:256
	flat_load_dword v165, v[128:129] offset:704
	v_add_u32_e32 v174, 0xb0, v164
	v_lshlrev_b32_e32 v128, 8, v174
	v_and_b32_e32 v176, 0x7ff00, v128
	v_lshl_add_u64 v[128:129], v[158:159], 0, v[176:177]
	flat_load_dwordx4 v[132:135], v[128:129]
	flat_load_dwordx4 v[136:139], v[128:129] offset:16
	v_lshl_add_u64 v[128:129], v[156:157], 0, v[176:177]
	flat_load_dwordx4 v[166:169], v[128:129]
	flat_load_dwordx4 v[170:173], v[128:129] offset:16
	v_mad_i64_i32 v[128:129], s[38:39], s82, v174, 0
	v_lshl_add_u64 v[128:129], v[128:129], 1, s[84:85]
	v_lshl_add_u64 v[128:129], v[128:129], 0, s[6:7]
	v_lshl_add_u64 v[178:179], v[128:129], 0, v[130:131]
	s_waitcnt vmcnt(0) lgkmcnt(0)
	v_fmamk_f32 v165, v165, 0x3a800000, v237
	v_rsq_f32_e32 v174, v165
	s_nop 0
	v_pk_mul_f32 v[128:129], v[20:21], v[174:175] op_sel_hi:[1,0]
	v_pk_mul_f32 v[130:131], v[22:23], v[174:175] op_sel_hi:[1,0]
	v_pk_mul_f32 v[182:183], v[16:17], v[174:175] op_sel_hi:[1,0]
	v_pk_mul_f32 v[184:185], v[18:19], v[174:175] op_sel_hi:[1,0]
	v_pk_mul_f32 v[186:187], v[4:5], v[174:175] op_sel_hi:[1,0]
	v_pk_mul_f32 v[188:189], v[6:7], v[174:175] op_sel_hi:[1,0]
	v_pk_mul_f32 v[190:191], v[0:1], v[174:175] op_sel_hi:[1,0]
	v_pk_mul_f32 v[174:175], v[2:3], v[174:175] op_sel_hi:[1,0]
	v_pk_mul_f32 v[192:193], v[134:135], v[188:189]
	v_pk_mul_f32 v[194:195], v[132:133], v[186:187]
	v_pk_mul_f32 v[196:197], v[138:139], v[174:175]
	v_pk_mul_f32 v[198:199], v[136:137], v[190:191]
	v_pk_mul_f32 v[188:189], v[168:169], v[188:189]
	v_pk_mul_f32 v[186:187], v[166:167], v[186:187]
	v_pk_mul_f32 v[174:175], v[172:173], v[174:175]
	v_pk_mul_f32 v[190:191], v[170:171], v[190:191]
	v_pk_fma_f32 v[168:169], v[168:169], v[130:131], v[192:193] neg_lo:[0,0,1] neg_hi:[0,0,1]
	v_pk_fma_f32 v[166:167], v[166:167], v[128:129], v[194:195] neg_lo:[0,0,1] neg_hi:[0,0,1]
	v_pk_fma_f32 v[172:173], v[172:173], v[184:185], v[196:197] neg_lo:[0,0,1] neg_hi:[0,0,1]
	v_pk_fma_f32 v[170:171], v[170:171], v[182:183], v[198:199] neg_lo:[0,0,1] neg_hi:[0,0,1]
	v_pk_fma_f32 v[134:135], v[134:135], v[130:131], v[188:189]
	v_pk_fma_f32 v[132:133], v[132:133], v[128:129], v[186:187]
	v_pk_fma_f32 v[138:139], v[138:139], v[184:185], v[174:175]
	v_pk_fma_f32 v[136:137], v[136:137], v[182:183], v[190:191]
	v_cvt_pk_bf16_f32 v128, v166, v167
	v_cvt_pk_bf16_f32 v129, v168, v169
	v_cvt_pk_bf16_f32 v130, v170, v171
	v_cvt_pk_bf16_f32 v131, v172, v173
	v_cvt_pk_bf16_f32 v132, v132, v133
	v_cvt_pk_bf16_f32 v133, v134, v135
	v_cvt_pk_bf16_f32 v134, v136, v137
	v_cvt_pk_bf16_f32 v135, v138, v139
	global_store_dwordx4 v[178:179], v[128:131], off
	global_store_dwordx4 v[178:179], v[132:135], off offset:256

; __device__ __forceinline__ float silu_f(float v) { return v * sigm_f(v); }
;     __device__ __forceinline__ void operator()(const f32x4 (&acc)[2][2][4][2], const Unit& u, int wr, int wc, int fr, int fq) const {
;     ...
;         } else if (mode == M_SWIGLU) {
; #pragma unroll
;             for (int ai = 0; ai < 2; ++ai)
; #pragma unroll
;                 for (int m = 0; m < 4; ++m) { const int row = row0 + ai * HALF + m * 16; const float rsv = __builtin_amdgcn_rsqf(rs[row] * (1.0f / 1024.0f) + 1e-6f);
;                     f32x4 h0, h1;
; #pragma unroll
;                     for (int e = 0; e < 4; ++e) { h0[e] = silu_f(acc[ai][0][m][0][e] * rsv) * (acc[ai][1][m][0][e] * rsv); h1[e] = silu_f(acc[ai][0][m][1][e] * rsv) * (acc[ai][1][m][1][e] * rsv); }
;                     store8(O + (size_t)row * ldc + u.pn * HALF + cw, h0, h1); }
.LBB0_588:
	s_mov_b64 s[6:7], -1
	s_cmp_lt_i32 s37, 1
	v_lshlrev_b64 v[128:129], 1, v[148:149]
	v_or_b32_e32 v171, 16, v164
	v_or_b32_e32 v170, 32, v164
	v_or_b32_e32 v169, 48, v164
	v_add_u32_e32 v168, 0x80, v164
	v_add_u32_e32 v167, 0x90, v164
	v_add_u32_e32 v166, 0xa0, v164
	s_cbranch_scc1 .LBB0_590
	v_ashrrev_i32_e32 v165, 31, v164
	v_lshl_add_u64 v[130:131], v[164:165], 2, s[26:27]
	global_load_dword v246, v[130:131], off
	global_load_dword v247, v[130:131], off offset:64
	global_load_dword v248, v[130:131], off offset:128
	global_load_dword v249, v[130:131], off offset:192
	global_load_dword v250, v[130:131], off offset:512
	global_load_dword v252, v[130:131], off offset:576
	global_load_dword v253, v[130:131], off offset:640
	global_load_dword v255, v[130:131], off offset:704
	s_lshl_b32 s6, s40, 7
	s_ashr_i32 s7, s6, 31
	s_lshl_b64 s[6:7], s[6:7], 1
	v_add_u32_e32 v165, 0xb0, v164
	s_waitcnt vmcnt(0) lgkmcnt(0)
	v_fmamk_f32 v132, v246, 0x3a800000, v237
	v_rsq_f32_e32 v138, v132
	s_nop 0
	v_pk_mul_f32 v[132:133], v[124:125], v[138:139] op_sel_hi:[1,0]
	s_nop 0
	v_mul_f32_e32 v134, 0xbfb8aa3b, v132
	v_mul_f32_e32 v135, 0xbfb8aa3b, v133
	v_exp_f32_e32 v134, v134
	v_exp_f32_e32 v135, v135
	v_add_f32_e32 v134, 1.0, v134
	v_add_f32_e32 v135, 1.0, v135
	v_rcp_f32_e32 v134, v134
	v_rcp_f32_e32 v135, v135
	s_nop 0
	v_pk_mul_f32 v[132:133], v[132:133], v[134:135]
	v_pk_mul_f32 v[134:135], v[108:109], v[138:139] op_sel_hi:[1,0]
	s_nop 0
	v_pk_mul_f32 v[132:133], v[134:135], v[132:133]
	v_pk_mul_f32 v[134:135], v[120:121], v[138:139] op_sel_hi:[1,0]
	v_cvt_pk_bf16_f32 v132, v132, v133
	v_mul_f32_e32 v136, 0xbfb8aa3b, v134
	v_mul_f32_e32 v137, 0xbfb8aa3b, v135
	v_exp_f32_e32 v136, v136
	v_exp_f32_e32 v137, v137
	v_add_f32_e32 v136, 1.0, v136
	v_add_f32_e32 v137, 1.0, v137
	v_rcp_f32_e32 v136, v136
	v_rcp_f32_e32 v137, v137
	s_nop 0
	v_pk_mul_f32 v[134:135], v[134:135], v[136:137]
	v_pk_mul_f32 v[136:137], v[104:105], v[138:139] op_sel_hi:[1,0]
	s_nop 0
	v_pk_mul_f32 v[134:135], v[136:137], v[134:135]
	v_pk_mul_f32 v[136:137], v[126:127], v[138:139] op_sel_hi:[1,0]
	v_cvt_pk_bf16_f32 v134, v134, v135
	v_mul_f32_e32 v139, 0xbfb8aa3b, v136
	v_exp_f32_e32 v139, v139
	s_nop 0
	v_add_f32_e32 v139, 1.0, v139
	v_rcp_f32_e32 v172, v139
	v_mul_f32_e32 v139, 0xbfb8aa3b, v137
	v_exp_f32_e32 v139, v139
	s_nop 0
	v_add_f32_e32 v139, 1.0, v139
	v_rcp_f32_e32 v173, v139
	s_nop 0
	v_pk_mul_f32 v[136:137], v[136:137], v[172:173]
	v_pk_mul_f32 v[172:173], v[110:111], v[138:139] op_sel_hi:[1,0]
	s_nop 0
	v_pk_mul_f32 v[136:137], v[172:173], v[136:137]
	v_pk_mul_f32 v[172:173], v[122:123], v[138:139] op_sel_hi:[1,0]
	v_cvt_pk_bf16_f32 v133, v136, v137
	v_mul_f32_e32 v139, 0xbfb8aa3b, v172
	v_exp_f32_e32 v139, v139
	s_nop 0
	v_add_f32_e32 v139, 1.0, v139
	v_rcp_f32_e32 v174, v139
	v_mul_f32_e32 v139, 0xbfb8aa3b, v173
	v_exp_f32_e32 v139, v139
	s_nop 0
	v_add_f32_e32 v139, 1.0, v139
	v_rcp_f32_e32 v175, v139
	v_pk_mul_f32 v[138:139], v[106:107], v[138:139] op_sel_hi:[1,0]
	v_pk_mul_f32 v[172:173], v[172:173], v[174:175]
	s_nop 0
	v_pk_mul_f32 v[138:139], v[138:139], v[172:173]
	v_mad_i64_i32 v[172:173], s[38:39], s82, v164, 0
	v_lshl_add_u64 v[172:173], v[172:173], 1, s[84:85]
	v_lshl_add_u64 v[172:173], v[172:173], 0, s[6:7]
	v_lshl_add_u64 v[172:173], v[172:173], 0, v[128:129]
	v_cvt_pk_bf16_f32 v135, v138, v139
	global_store_dwordx4 v[172:173], v[132:135], off
	s_nop 1
	v_fmamk_f32 v132, v247, 0x3a800000, v237
	v_rsq_f32_e32 v138, v132
	s_nop 0
	v_pk_mul_f32 v[132:133], v[116:117], v[138:139] op_sel_hi:[1,0]
	s_nop 0
	v_mul_f32_e32 v134, 0xbfb8aa3b, v132
	v_mul_f32_e32 v135, 0xbfb8aa3b, v133
	v_exp_f32_e32 v134, v134
	v_exp_f32_e32 v135, v135
	v_add_f32_e32 v134, 1.0, v134
	v_add_f32_e32 v135, 1.0, v135
	v_rcp_f32_e32 v134, v134
	v_rcp_f32_e32 v135, v135
	s_nop 0
	v_pk_mul_f32 v[132:133], v[132:133], v[134:135]
	v_pk_mul_f32 v[134:135], v[92:93], v[138:139] op_sel_hi:[1,0]
	s_nop 0
	v_pk_mul_f32 v[132:133], v[134:135], v[132:133]
	v_pk_mul_f32 v[134:135], v[112:113], v[138:139] op_sel_hi:[1,0]
	v_cvt_pk_bf16_f32 v132, v132, v133
	v_mul_f32_e32 v136, 0xbfb8aa3b, v134
	v_mul_f32_e32 v137, 0xbfb8aa3b, v135
	v_exp_f32_e32 v136, v136
	v_exp_f32_e32 v137, v137
	v_add_f32_e32 v136, 1.0, v136
	v_add_f32_e32 v137, 1.0, v137
	v_rcp_f32_e32 v136, v136
	v_rcp_f32_e32 v137, v137
	s_nop 0
	v_pk_mul_f32 v[134:135], v[134:135], v[136:137]
	v_pk_mul_f32 v[136:137], v[88:89], v[138:139] op_sel_hi:[1,0]
	s_nop 0
	v_pk_mul_f32 v[134:135], v[136:137], v[134:135]
	v_pk_mul_f32 v[136:137], v[118:119], v[138:139] op_sel_hi:[1,0]
	v_cvt_pk_bf16_f32 v134, v134, v135
	v_mul_f32_e32 v139, 0xbfb8aa3b, v136
	v_exp_f32_e32 v139, v139
	s_nop 0
	v_add_f32_e32 v139, 1.0, v139
	v_rcp_f32_e32 v172, v139
	v_mul_f32_e32 v139, 0xbfb8aa3b, v137
	v_exp_f32_e32 v139, v139
	s_nop 0
	v_add_f32_e32 v139, 1.0, v139
	v_rcp_f32_e32 v173, v139
	s_nop 0
	v_pk_mul_f32 v[136:137], v[136:137], v[172:173]
	v_pk_mul_f32 v[172:173], v[94:95], v[138:139] op_sel_hi:[1,0]
	s_nop 0
	v_pk_mul_f32 v[136:137], v[172:173], v[136:137]
	v_pk_mul_f32 v[172:173], v[114:115], v[138:139] op_sel_hi:[1,0]
	v_cvt_pk_bf16_f32 v133, v136, v137
	v_mul_f32_e32 v139, 0xbfb8aa3b, v172
	v_exp_f32_e32 v139, v139
	s_nop 0
	v_add_f32_e32 v139, 1.0, v139
	v_rcp_f32_e32 v174, v139
	v_mul_f32_e32 v139, 0xbfb8aa3b, v173
	v_exp_f32_e32 v139, v139
	s_nop 0
	v_add_f32_e32 v139, 1.0, v139
	v_rcp_f32_e32 v175, v139
	v_pk_mul_f32 v[138:139], v[90:91], v[138:139] op_sel_hi:[1,0]
	v_pk_mul_f32 v[172:173], v[172:173], v[174:175]
	s_nop 0
	v_pk_mul_f32 v[138:139], v[138:139], v[172:173]
	v_mad_i64_i32 v[172:173], s[38:39], s82, v171, 0
; __device__ __forceinline__ float silu_f(float v) { return v * sigm_f(v); }
;     __device__ __forceinline__ void operator()(const f32x4 (&acc)[2][2][4][2], const Unit& u, int wr, int wc, int fr, int fq) const {
;     ...
; #pragma unroll
;             for (int ai = 0; ai < 2; ++ai)
; #pragma unroll
;                 for (int m = 0; m < 4; ++m) { const int row = row0 + ai * HALF + m * 16; const float rsv = __builtin_amdgcn_rsqf(rs[row] * (1.0f / 1024.0f) + 1e-6f);
;                     f32x4 h0, h1;
; #pragma unroll
;                     for (int e = 0; e < 4; ++e) { h0[e] = silu_f(acc[ai][0][m][0][e] * rsv) * (acc[ai][1][m][0][e] * rsv); h1[e] = silu_f(acc[ai][0][m][1][e] * rsv) * (acc[ai][1][m][1][e] * rsv); }
;                     store8(O + (size_t)row * ldc + u.pn * HALF + cw, h0, h1); }
	v_lshl_add_u64 v[172:173], v[172:173], 1, s[84:85]
	v_lshl_add_u64 v[172:173], v[172:173], 0, s[6:7]
	v_lshl_add_u64 v[172:173], v[172:173], 0, v[128:129]
	v_cvt_pk_bf16_f32 v135, v138, v139
	global_store_dwordx4 v[172:173], v[132:135], off
	s_nop 1
	v_fmamk_f32 v132, v248, 0x3a800000, v237
	v_rsq_f32_e32 v138, v132
	s_nop 0
	v_pk_mul_f32 v[132:133], v[100:101], v[138:139] op_sel_hi:[1,0]
	s_nop 0
	v_mul_f32_e32 v134, 0xbfb8aa3b, v132
	v_mul_f32_e32 v135, 0xbfb8aa3b, v133
	v_exp_f32_e32 v134, v134
	v_exp_f32_e32 v135, v135
	v_add_f32_e32 v134, 1.0, v134
	v_add_f32_e32 v135, 1.0, v135
	v_rcp_f32_e32 v134, v134
	v_rcp_f32_e32 v135, v135
	s_nop 0
	v_pk_mul_f32 v[132:133], v[132:133], v[134:135]
	v_pk_mul_f32 v[134:135], v[76:77], v[138:139] op_sel_hi:[1,0]
	s_nop 0
	v_pk_mul_f32 v[132:133], v[134:135], v[132:133]
	v_pk_mul_f32 v[134:135], v[96:97], v[138:139] op_sel_hi:[1,0]
	v_cvt_pk_bf16_f32 v132, v132, v133
	v_mul_f32_e32 v136, 0xbfb8aa3b, v134
	v_mul_f32_e32 v137, 0xbfb8aa3b, v135
	v_exp_f32_e32 v136, v136
	v_exp_f32_e32 v137, v137
	v_add_f32_e32 v136, 1.0, v136
	v_add_f32_e32 v137, 1.0, v137
	v_rcp_f32_e32 v136, v136
	v_rcp_f32_e32 v137, v137
	s_nop 0
	v_pk_mul_f32 v[134:135], v[134:135], v[136:137]
	v_pk_mul_f32 v[136:137], v[72:73], v[138:139] op_sel_hi:[1,0]
	s_nop 0
	v_pk_mul_f32 v[134:135], v[136:137], v[134:135]
	v_pk_mul_f32 v[136:137], v[102:103], v[138:139] op_sel_hi:[1,0]
	v_cvt_pk_bf16_f32 v134, v134, v135
	v_mul_f32_e32 v139, 0xbfb8aa3b, v136
	v_exp_f32_e32 v139, v139
	s_nop 0
	v_add_f32_e32 v139, 1.0, v139
	v_rcp_f32_e32 v172, v139
	v_mul_f32_e32 v139, 0xbfb8aa3b, v137
	v_exp_f32_e32 v139, v139
	s_nop 0
	v_add_f32_e32 v139, 1.0, v139
	v_rcp_f32_e32 v173, v139
	s_nop 0
	v_pk_mul_f32 v[136:137], v[136:137], v[172:173]
	v_pk_mul_f32 v[172:173], v[78:79], v[138:139] op_sel_hi:[1,0]
	s_nop 0
	v_pk_mul_f32 v[136:137], v[172:173], v[136:137]
	v_pk_mul_f32 v[172:173], v[98:99], v[138:139] op_sel_hi:[1,0]
	v_cvt_pk_bf16_f32 v133, v136, v137
	v_mul_f32_e32 v139, 0xbfb8aa3b, v172
	v_exp_f32_e32 v139, v139
	s_nop 0
	v_add_f32_e32 v139, 1.0, v139
	v_rcp_f32_e32 v174, v139
	v_mul_f32_e32 v139, 0xbfb8aa3b, v173
	v_exp_f32_e32 v139, v139
	s_nop 0
	v_add_f32_e32 v139, 1.0, v139
	v_rcp_f32_e32 v175, v139
	v_pk_mul_f32 v[138:139], v[74:75], v[138:139] op_sel_hi:[1,0]
	v_pk_mul_f32 v[172:173], v[172:173], v[174:175]
	s_nop 0
	v_pk_mul_f32 v[138:139], v[138:139], v[172:173]
	v_mad_i64_i32 v[172:173], s[38:39], s82, v170, 0
	v_lshl_add_u64 v[172:173], v[172:173], 1, s[84:85]
	v_lshl_add_u64 v[172:173], v[172:173], 0, s[6:7]
	v_lshl_add_u64 v[172:173], v[172:173], 0, v[128:129]
	v_cvt_pk_bf16_f32 v135, v138, v139
	global_store_dwordx4 v[172:173], v[132:135], off
	s_nop 1
	v_fmamk_f32 v132, v249, 0x3a800000, v237
	v_rsq_f32_e32 v138, v132
	s_nop 0
	v_pk_mul_f32 v[132:133], v[84:85], v[138:139] op_sel_hi:[1,0]
	s_nop 0
	v_mul_f32_e32 v134, 0xbfb8aa3b, v132
	v_mul_f32_e32 v135, 0xbfb8aa3b, v133
	v_exp_f32_e32 v134, v134
	v_exp_f32_e32 v135, v135
	v_add_f32_e32 v134, 1.0, v134
	v_add_f32_e32 v135, 1.0, v135
	v_rcp_f32_e32 v134, v134
	v_rcp_f32_e32 v135, v135
	s_nop 0
	v_pk_mul_f32 v[132:133], v[132:133], v[134:135]
	v_pk_mul_f32 v[134:135], v[68:69], v[138:139] op_sel_hi:[1,0]
	s_nop 0
	v_pk_mul_f32 v[132:133], v[134:135], v[132:133]
	v_pk_mul_f32 v[134:135], v[80:81], v[138:139] op_sel_hi:[1,0]
	v_cvt_pk_bf16_f32 v132, v132, v133
	v_mul_f32_e32 v136, 0xbfb8aa3b, v134
	v_mul_f32_e32 v137, 0xbfb8aa3b, v135
	v_exp_f32_e32 v136, v136
	v_exp_f32_e32 v137, v137
	v_add_f32_e32 v136, 1.0, v136
	v_add_f32_e32 v137, 1.0, v137
	v_rcp_f32_e32 v136, v136
	v_rcp_f32_e32 v137, v137
	s_nop 0
	v_pk_mul_f32 v[134:135], v[134:135], v[136:137]
	v_pk_mul_f32 v[136:137], v[64:65], v[138:139] op_sel_hi:[1,0]
	s_nop 0
	v_pk_mul_f32 v[134:135], v[136:137], v[134:135]
	v_pk_mul_f32 v[136:137], v[86:87], v[138:139] op_sel_hi:[1,0]
	v_cvt_pk_bf16_f32 v134, v134, v135
	v_mul_f32_e32 v139, 0xbfb8aa3b, v136
	v_exp_f32_e32 v139, v139
	s_nop 0
	v_add_f32_e32 v139, 1.0, v139
	v_rcp_f32_e32 v172, v139
	v_mul_f32_e32 v139, 0xbfb8aa3b, v137
	v_exp_f32_e32 v139, v139
	s_nop 0
	v_add_f32_e32 v139, 1.0, v139
	v_rcp_f32_e32 v173, v139
	s_nop 0
	v_pk_mul_f32 v[136:137], v[136:137], v[172:173]
	v_pk_mul_f32 v[172:173], v[70:71], v[138:139] op_sel_hi:[1,0]
	s_nop 0
	v_pk_mul_f32 v[136:137], v[172:173], v[136:137]
	v_pk_mul_f32 v[172:173], v[82:83], v[138:139] op_sel_hi:[1,0]
	v_cvt_pk_bf16_f32 v133, v136, v137
	v_mul_f32_e32 v139, 0xbfb8aa3b, v172
	v_exp_f32_e32 v139, v139
	s_nop 0
	v_add_f32_e32 v139, 1.0, v139
	v_rcp_f32_e32 v174, v139
	v_mul_f32_e32 v139, 0xbfb8aa3b, v173
	v_exp_f32_e32 v139, v139
	s_nop 0
	v_add_f32_e32 v139, 1.0, v139
	v_rcp_f32_e32 v175, v139
	v_pk_mul_f32 v[138:139], v[66:67], v[138:139] op_sel_hi:[1,0]
	v_pk_mul_f32 v[172:173], v[172:173], v[174:175]
	s_nop 0
	v_pk_mul_f32 v[138:139], v[138:139], v[172:173]
	v_mad_i64_i32 v[172:173], s[38:39], s82, v169, 0
	v_lshl_add_u64 v[172:173], v[172:173], 1, s[84:85]
	v_lshl_add_u64 v[172:173], v[172:173], 0, s[6:7]
	v_lshl_add_u64 v[172:173], v[172:173], 0, v[128:129]
	v_cvt_pk_bf16_f32 v135, v138, v139
	global_store_dwordx4 v[172:173], v[132:135], off
	s_nop 1
	v_fmamk_f32 v132, v250, 0x3a800000, v237
	v_rsq_f32_e32 v138, v132
	s_nop 0
	v_pk_mul_f32 v[132:133], v[60:61], v[138:139] op_sel_hi:[1,0]
	s_nop 0
	v_mul_f32_e32 v134, 0xbfb8aa3b, v132
	v_mul_f32_e32 v135, 0xbfb8aa3b, v133
	v_exp_f32_e32 v134, v134
	v_exp_f32_e32 v135, v135
	v_add_f32_e32 v134, 1.0, v134
	v_add_f32_e32 v135, 1.0, v135
	v_rcp_f32_e32 v134, v134
	v_rcp_f32_e32 v135, v135
	s_nop 0
	v_pk_mul_f32 v[132:133], v[132:133], v[134:135]
; __device__ __forceinline__ float silu_f(float v) { return v * sigm_f(v); }
;     __device__ __forceinline__ void operator()(const f32x4 (&acc)[2][2][4][2], const Unit& u, int wr, int wc, int fr, int fq) const {
;     ...
; #pragma unroll
;             for (int ai = 0; ai < 2; ++ai)
; #pragma unroll
;                 for (int m = 0; m < 4; ++m) { const int row = row0 + ai * HALF + m * 16; const float rsv = __builtin_amdgcn_rsqf(rs[row] * (1.0f / 1024.0f) + 1e-6f);
;                     f32x4 h0, h1;
; #pragma unroll
;                     for (int e = 0; e < 4; ++e) { h0[e] = silu_f(acc[ai][0][m][0][e] * rsv) * (acc[ai][1][m][0][e] * rsv); h1[e] = silu_f(acc[ai][0][m][1][e] * rsv) * (acc[ai][1][m][1][e] * rsv); }
;                     store8(O + (size_t)row * ldc + u.pn * HALF + cw, h0, h1); }
	v_pk_mul_f32 v[134:135], v[44:45], v[138:139] op_sel_hi:[1,0]
	s_nop 0
	v_pk_mul_f32 v[132:133], v[134:135], v[132:133]
	v_pk_mul_f32 v[134:135], v[56:57], v[138:139] op_sel_hi:[1,0]
	v_cvt_pk_bf16_f32 v132, v132, v133
	v_mul_f32_e32 v136, 0xbfb8aa3b, v134
	v_mul_f32_e32 v137, 0xbfb8aa3b, v135
	v_exp_f32_e32 v136, v136
	v_exp_f32_e32 v137, v137
	v_add_f32_e32 v136, 1.0, v136
	v_add_f32_e32 v137, 1.0, v137
	v_rcp_f32_e32 v136, v136
	v_rcp_f32_e32 v137, v137
	s_nop 0
	v_pk_mul_f32 v[134:135], v[134:135], v[136:137]
	v_pk_mul_f32 v[136:137], v[40:41], v[138:139] op_sel_hi:[1,0]
	s_nop 0
	v_pk_mul_f32 v[134:135], v[136:137], v[134:135]
	v_pk_mul_f32 v[136:137], v[62:63], v[138:139] op_sel_hi:[1,0]
	v_cvt_pk_bf16_f32 v134, v134, v135
	v_mul_f32_e32 v139, 0xbfb8aa3b, v136
	v_exp_f32_e32 v139, v139
	s_nop 0
	v_add_f32_e32 v139, 1.0, v139
	v_rcp_f32_e32 v172, v139
	v_mul_f32_e32 v139, 0xbfb8aa3b, v137
	v_exp_f32_e32 v139, v139
	s_nop 0
	v_add_f32_e32 v139, 1.0, v139
	v_rcp_f32_e32 v173, v139
	s_nop 0
	v_pk_mul_f32 v[136:137], v[136:137], v[172:173]
	v_pk_mul_f32 v[172:173], v[46:47], v[138:139] op_sel_hi:[1,0]
	s_nop 0
	v_pk_mul_f32 v[136:137], v[172:173], v[136:137]
	v_pk_mul_f32 v[172:173], v[58:59], v[138:139] op_sel_hi:[1,0]
	v_cvt_pk_bf16_f32 v133, v136, v137
	v_mul_f32_e32 v139, 0xbfb8aa3b, v172
	v_exp_f32_e32 v139, v139
	s_nop 0
	v_add_f32_e32 v139, 1.0, v139
	v_rcp_f32_e32 v174, v139
	v_mul_f32_e32 v139, 0xbfb8aa3b, v173
	v_exp_f32_e32 v139, v139
	s_nop 0
	v_add_f32_e32 v139, 1.0, v139
	v_rcp_f32_e32 v175, v139
	v_pk_mul_f32 v[138:139], v[42:43], v[138:139] op_sel_hi:[1,0]
	v_pk_mul_f32 v[172:173], v[172:173], v[174:175]
	s_nop 0
	v_pk_mul_f32 v[138:139], v[138:139], v[172:173]
	v_mad_i64_i32 v[172:173], s[38:39], s82, v168, 0
	v_lshl_add_u64 v[172:173], v[172:173], 1, s[84:85]
	v_lshl_add_u64 v[172:173], v[172:173], 0, s[6:7]
	v_lshl_add_u64 v[172:173], v[172:173], 0, v[128:129]
	v_cvt_pk_bf16_f32 v135, v138, v139
	global_store_dwordx4 v[172:173], v[132:135], off
	s_nop 1
	v_fmamk_f32 v132, v252, 0x3a800000, v237
	v_rsq_f32_e32 v138, v132
	s_nop 0
	v_pk_mul_f32 v[132:133], v[52:53], v[138:139] op_sel_hi:[1,0]
	s_nop 0
	v_mul_f32_e32 v134, 0xbfb8aa3b, v132
	v_mul_f32_e32 v135, 0xbfb8aa3b, v133
	v_exp_f32_e32 v134, v134
	v_exp_f32_e32 v135, v135
	v_add_f32_e32 v134, 1.0, v134
	v_add_f32_e32 v135, 1.0, v135
	v_rcp_f32_e32 v134, v134
	v_rcp_f32_e32 v135, v135
	s_nop 0
	v_pk_mul_f32 v[132:133], v[132:133], v[134:135]
	v_pk_mul_f32 v[134:135], v[28:29], v[138:139] op_sel_hi:[1,0]
	s_nop 0
	v_pk_mul_f32 v[132:133], v[134:135], v[132:133]
	v_pk_mul_f32 v[134:135], v[48:49], v[138:139] op_sel_hi:[1,0]
	v_cvt_pk_bf16_f32 v132, v132, v133
	v_mul_f32_e32 v136, 0xbfb8aa3b, v134
	v_mul_f32_e32 v137, 0xbfb8aa3b, v135
	v_exp_f32_e32 v136, v136
	v_exp_f32_e32 v137, v137
	v_add_f32_e32 v136, 1.0, v136
	v_add_f32_e32 v137, 1.0, v137
	v_rcp_f32_e32 v136, v136
	v_rcp_f32_e32 v137, v137
	s_nop 0
	v_pk_mul_f32 v[134:135], v[134:135], v[136:137]
	v_pk_mul_f32 v[136:137], v[24:25], v[138:139] op_sel_hi:[1,0]
	s_nop 0
	v_pk_mul_f32 v[134:135], v[136:137], v[134:135]
	v_pk_mul_f32 v[136:137], v[54:55], v[138:139] op_sel_hi:[1,0]
	v_cvt_pk_bf16_f32 v134, v134, v135
	v_mul_f32_e32 v139, 0xbfb8aa3b, v136
	v_exp_f32_e32 v139, v139
	s_nop 0
	v_add_f32_e32 v139, 1.0, v139
	v_rcp_f32_e32 v172, v139
	v_mul_f32_e32 v139, 0xbfb8aa3b, v137
	v_exp_f32_e32 v139, v139
	s_nop 0
	v_add_f32_e32 v139, 1.0, v139
	v_rcp_f32_e32 v173, v139
	s_nop 0
	v_pk_mul_f32 v[136:137], v[136:137], v[172:173]
	v_pk_mul_f32 v[172:173], v[30:31], v[138:139] op_sel_hi:[1,0]
	s_nop 0
	v_pk_mul_f32 v[136:137], v[172:173], v[136:137]
	v_pk_mul_f32 v[172:173], v[50:51], v[138:139] op_sel_hi:[1,0]
	v_cvt_pk_bf16_f32 v133, v136, v137
	v_mul_f32_e32 v139, 0xbfb8aa3b, v172
	v_exp_f32_e32 v139, v139
	s_nop 0
	v_add_f32_e32 v139, 1.0, v139
	v_rcp_f32_e32 v174, v139
	v_mul_f32_e32 v139, 0xbfb8aa3b, v173
	v_exp_f32_e32 v139, v139
	s_nop 0
	v_add_f32_e32 v139, 1.0, v139
	v_rcp_f32_e32 v175, v139
	v_pk_mul_f32 v[138:139], v[26:27], v[138:139] op_sel_hi:[1,0]
	v_pk_mul_f32 v[172:173], v[172:173], v[174:175]
	s_nop 0
	v_pk_mul_f32 v[138:139], v[138:139], v[172:173]
	v_mad_i64_i32 v[172:173], s[38:39], s82, v167, 0
	v_lshl_add_u64 v[172:173], v[172:173], 1, s[84:85]
	v_lshl_add_u64 v[172:173], v[172:173], 0, s[6:7]
	v_lshl_add_u64 v[172:173], v[172:173], 0, v[128:129]
	v_cvt_pk_bf16_f32 v135, v138, v139
	global_store_dwordx4 v[172:173], v[132:135], off
	s_nop 1
	v_fmamk_f32 v132, v253, 0x3a800000, v237
	v_rsq_f32_e32 v138, v132
	s_nop 0
	v_pk_mul_f32 v[132:133], v[36:37], v[138:139] op_sel_hi:[1,0]
	s_nop 0
	v_mul_f32_e32 v134, 0xbfb8aa3b, v132
	v_mul_f32_e32 v135, 0xbfb8aa3b, v133
; __device__ __forceinline__ float silu_f(float v) { return v * sigm_f(v); }
;     __device__ __forceinline__ void operator()(const f32x4 (&acc)[2][2][4][2], const Unit& u, int wr, int wc, int fr, int fq) const {
;     ...
; #pragma unroll
;             for (int ai = 0; ai < 2; ++ai)
; #pragma unroll
;                 for (int m = 0; m < 4; ++m) { const int row = row0 + ai * HALF + m * 16; const float rsv = __builtin_amdgcn_rsqf(rs[row] * (1.0f / 1024.0f) + 1e-6f);
;                     f32x4 h0, h1;
; #pragma unroll
;                     for (int e = 0; e < 4; ++e) { h0[e] = silu_f(acc[ai][0][m][0][e] * rsv) * (acc[ai][1][m][0][e] * rsv); h1[e] = silu_f(acc[ai][0][m][1][e] * rsv) * (acc[ai][1][m][1][e] * rsv); }
;                     store8(O + (size_t)row * ldc + u.pn * HALF + cw, h0, h1); }
	v_exp_f32_e32 v134, v134
	v_exp_f32_e32 v135, v135
	v_add_f32_e32 v134, 1.0, v134
	v_add_f32_e32 v135, 1.0, v135
	v_rcp_f32_e32 v134, v134
	v_rcp_f32_e32 v135, v135
	s_nop 0
	v_pk_mul_f32 v[132:133], v[132:133], v[134:135]
	v_pk_mul_f32 v[134:135], v[12:13], v[138:139] op_sel_hi:[1,0]
	s_nop 0
	v_pk_mul_f32 v[132:133], v[134:135], v[132:133]
	v_pk_mul_f32 v[134:135], v[32:33], v[138:139] op_sel_hi:[1,0]
	v_cvt_pk_bf16_f32 v132, v132, v133
	v_mul_f32_e32 v136, 0xbfb8aa3b, v134
	v_mul_f32_e32 v137, 0xbfb8aa3b, v135
	v_exp_f32_e32 v136, v136
	v_exp_f32_e32 v137, v137
	v_add_f32_e32 v136, 1.0, v136
	v_add_f32_e32 v137, 1.0, v137
	v_rcp_f32_e32 v136, v136
	v_rcp_f32_e32 v137, v137
	s_nop 0
	v_pk_mul_f32 v[134:135], v[134:135], v[136:137]
	v_pk_mul_f32 v[136:137], v[8:9], v[138:139] op_sel_hi:[1,0]
	s_nop 0
	v_pk_mul_f32 v[134:135], v[136:137], v[134:135]
	v_pk_mul_f32 v[136:137], v[38:39], v[138:139] op_sel_hi:[1,0]
	v_cvt_pk_bf16_f32 v134, v134, v135
	v_mul_f32_e32 v139, 0xbfb8aa3b, v136
	v_exp_f32_e32 v139, v139
	s_nop 0
	v_add_f32_e32 v139, 1.0, v139
	v_rcp_f32_e32 v172, v139
	v_mul_f32_e32 v139, 0xbfb8aa3b, v137
	v_exp_f32_e32 v139, v139
	s_nop 0
	v_add_f32_e32 v139, 1.0, v139
	v_rcp_f32_e32 v173, v139
	s_nop 0
	v_pk_mul_f32 v[136:137], v[136:137], v[172:173]
	v_pk_mul_f32 v[172:173], v[14:15], v[138:139] op_sel_hi:[1,0]
	s_nop 0
	v_pk_mul_f32 v[136:137], v[172:173], v[136:137]
	v_pk_mul_f32 v[172:173], v[34:35], v[138:139] op_sel_hi:[1,0]
	v_cvt_pk_bf16_f32 v133, v136, v137
	v_mul_f32_e32 v139, 0xbfb8aa3b, v172
	v_exp_f32_e32 v139, v139
	s_nop 0
	v_add_f32_e32 v139, 1.0, v139
	v_rcp_f32_e32 v174, v139
	v_mul_f32_e32 v139, 0xbfb8aa3b, v173
	v_exp_f32_e32 v139, v139
	s_nop 0
	v_add_f32_e32 v139, 1.0, v139
	v_rcp_f32_e32 v175, v139
	v_pk_mul_f32 v[138:139], v[10:11], v[138:139] op_sel_hi:[1,0]
	v_pk_mul_f32 v[172:173], v[172:173], v[174:175]
	s_nop 0
	v_pk_mul_f32 v[138:139], v[138:139], v[172:173]
	v_mad_i64_i32 v[172:173], s[38:39], s82, v166, 0
	v_lshl_add_u64 v[172:173], v[172:173], 1, s[84:85]
	v_lshl_add_u64 v[172:173], v[172:173], 0, s[6:7]
	v_lshl_add_u64 v[172:173], v[172:173], 0, v[128:129]
	v_cvt_pk_bf16_f32 v135, v138, v139
	global_store_dwordx4 v[172:173], v[132:135], off
	s_nop 1
	v_fmamk_f32 v130, v255, 0x3a800000, v237
	v_rsq_f32_e32 v136, v130
	s_nop 0
	v_pk_mul_f32 v[130:131], v[20:21], v[136:137] op_sel_hi:[1,0]
	s_nop 0
	v_mul_f32_e32 v132, 0xbfb8aa3b, v130
	v_mul_f32_e32 v133, 0xbfb8aa3b, v131
	v_exp_f32_e32 v132, v132
	v_exp_f32_e32 v133, v133
	v_add_f32_e32 v132, 1.0, v132
	v_add_f32_e32 v133, 1.0, v133
	v_rcp_f32_e32 v132, v132
	v_rcp_f32_e32 v133, v133
	s_nop 0
	v_pk_mul_f32 v[130:131], v[130:131], v[132:133]
	v_pk_mul_f32 v[132:133], v[4:5], v[136:137] op_sel_hi:[1,0]
	s_nop 0
	v_pk_mul_f32 v[130:131], v[132:133], v[130:131]
	v_pk_mul_f32 v[132:133], v[16:17], v[136:137] op_sel_hi:[1,0]
	v_cvt_pk_bf16_f32 v130, v130, v131
	v_mul_f32_e32 v134, 0xbfb8aa3b, v132
	v_mul_f32_e32 v135, 0xbfb8aa3b, v133
	v_exp_f32_e32 v134, v134
	v_exp_f32_e32 v135, v135
	v_add_f32_e32 v134, 1.0, v134
	v_add_f32_e32 v135, 1.0, v135
	v_rcp_f32_e32 v134, v134
	v_rcp_f32_e32 v135, v135
	s_nop 0
	v_pk_mul_f32 v[132:133], v[132:133], v[134:135]
	v_pk_mul_f32 v[134:135], v[0:1], v[136:137] op_sel_hi:[1,0]
	s_nop 0
	v_pk_mul_f32 v[132:133], v[134:135], v[132:133]
	v_pk_mul_f32 v[134:135], v[22:23], v[136:137] op_sel_hi:[1,0]
	v_cvt_pk_bf16_f32 v132, v132, v133
	v_mul_f32_e32 v137, 0xbfb8aa3b, v134
	v_exp_f32_e32 v137, v137
	s_nop 0
	v_add_f32_e32 v137, 1.0, v137
	v_rcp_f32_e32 v138, v137
	v_mul_f32_e32 v137, 0xbfb8aa3b, v135
	v_exp_f32_e32 v137, v137
	s_nop 0
	v_add_f32_e32 v137, 1.0, v137
	v_rcp_f32_e32 v139, v137
	s_nop 0
	v_pk_mul_f32 v[134:135], v[134:135], v[138:139]
	v_pk_mul_f32 v[138:139], v[6:7], v[136:137] op_sel_hi:[1,0]
	s_nop 0
	v_pk_mul_f32 v[134:135], v[138:139], v[134:135]
	v_pk_mul_f32 v[138:139], v[18:19], v[136:137] op_sel_hi:[1,0]
	v_cvt_pk_bf16_f32 v131, v134, v135
	v_mul_f32_e32 v137, 0xbfb8aa3b, v138
	v_exp_f32_e32 v137, v137
	s_nop 0
	v_add_f32_e32 v137, 1.0, v137
	v_rcp_f32_e32 v172, v137
	v_mul_f32_e32 v137, 0xbfb8aa3b, v139
	v_exp_f32_e32 v137, v137
	s_nop 0
	v_add_f32_e32 v137, 1.0, v137
	v_rcp_f32_e32 v173, v137
	v_pk_mul_f32 v[136:137], v[2:3], v[136:137] op_sel_hi:[1,0]
	v_pk_mul_f32 v[138:139], v[138:139], v[172:173]
	s_nop 0
	v_pk_mul_f32 v[136:137], v[136:137], v[138:139]
	v_mad_i64_i32 v[138:139], s[38:39], s82, v165, 0
	v_lshl_add_u64 v[138:139], v[138:139], 1, s[84:85]
	v_lshl_add_u64 v[138:139], v[138:139], 0, s[6:7]
	v_lshl_add_u64 v[138:139], v[138:139], 0, v[128:129]
	v_cvt_pk_bf16_f32 v133, v136, v137
	s_mov_b64 s[6:7], 0
	global_store_dwordx4 v[138:139], v[130:133], off
